# K-loops: end-of-load-section waits merged into one s_waitcnt vmcnt(N) lgkmcnt(0) (28 sites); on top of R3
# baseline (speedup 1.0000x reference)
.LBB0_904:
	s_add_i32 s69, s8, 2
	s_add_u32 s0, s52, 0xfff80080
	s_addc_u32 s1, s53, -1
	s_add_i32 s70, 0, 0x10000
	s_cmp_eq_u32 s66, s8
	s_cselect_b32 s59, s41, s1
	s_cselect_b32 s58, s45, s0
	s_cselect_b32 s9, s43, s68
	s_cselect_b32 s8, s65, s67
	s_add_i32 s0, 0, 0x14000
	v_add_u32_e32 v156, s70, v141
	v_add_u32_e32 v172, s0, v141
	ds_read_b128 v[144:147], v156
	ds_read_b128 v[148:151], v156 offset:1024
	ds_read_b128 v[152:155], v156 offset:2048
	ds_read_b128 v[156:159], v156 offset:3072
	ds_read_b128 v[160:163], v172
	ds_read_b128 v[164:167], v172 offset:1024
	ds_read_b128 v[168:171], v172 offset:2048
	ds_read_b128 v[172:175], v172 offset:3072
	v_lshl_add_u64 v[214:215], s[52:53], 0, v[138:139]
	s_add_i32 m0, s27, 0xc000
	ds_read_b128 v[176:179], v143
	ds_read_b128 v[180:183], v143 offset:1024
	ds_read_b128 v[184:187], v143 offset:2048
	ds_read_b128 v[188:191], v143 offset:3072
	ds_read_b128 v[192:195], v143 offset:4096
	ds_read_b128 v[202:205], v143 offset:5120
	ds_read_b128 v[206:209], v143 offset:6144
	ds_read_b128 v[210:213], v143 offset:7168
	global_load_lds_dwordx4 v[214:215], off
	v_lshl_add_u64 v[214:215], s[52:53], 0, v[136:137]
	s_add_i32 m0, s27, 0xe000
	s_nop 0
	global_load_lds_dwordx4 v[214:215], off
	s_waitcnt vmcnt(8) lgkmcnt(0)
	s_setprio 1
	s_barrier
	v_mfma_f32_16x16x32_bf16 v[126:129], v[144:147], v[176:179], v[126:129]
	v_mfma_f32_16x16x32_bf16 v[118:121], v[152:155], v[176:179], v[118:121]
	v_mfma_f32_16x16x32_bf16 v[110:113], v[144:147], v[184:187], v[110:113]
	v_mfma_f32_16x16x32_bf16 v[102:105], v[152:155], v[184:187], v[102:105]
	v_mfma_f32_16x16x32_bf16 v[94:97], v[144:147], v[192:195], v[94:97]
	v_mfma_f32_16x16x32_bf16 v[86:89], v[152:155], v[192:195], v[86:89]
	v_mfma_f32_16x16x32_bf16 v[78:81], v[144:147], v[206:209], v[78:81]
	v_mfma_f32_16x16x32_bf16 v[70:73], v[152:155], v[206:209], v[70:73]
	v_mfma_f32_16x16x32_bf16 v[126:129], v[148:151], v[180:183], v[126:129]
	v_mfma_f32_16x16x32_bf16 v[118:121], v[156:159], v[180:183], v[118:121]
	v_mfma_f32_16x16x32_bf16 v[110:113], v[148:151], v[188:191], v[110:113]
	v_mfma_f32_16x16x32_bf16 v[102:105], v[156:159], v[188:191], v[102:105]
	v_mfma_f32_16x16x32_bf16 v[94:97], v[148:151], v[202:205], v[94:97]
	v_mfma_f32_16x16x32_bf16 v[86:89], v[156:159], v[202:205], v[86:89]
	v_mfma_f32_16x16x32_bf16 v[78:81], v[148:151], v[210:213], v[78:81]
	v_mfma_f32_16x16x32_bf16 v[70:73], v[156:159], v[210:213], v[70:73]
	v_mfma_f32_16x16x32_bf16 v[122:125], v[160:163], v[176:179], v[122:125]
	v_mfma_f32_16x16x32_bf16 v[114:117], v[168:171], v[176:179], v[114:117]
	v_mfma_f32_16x16x32_bf16 v[106:109], v[160:163], v[184:187], v[106:109]
	v_mfma_f32_16x16x32_bf16 v[98:101], v[168:171], v[184:187], v[98:101]
	v_mfma_f32_16x16x32_bf16 v[90:93], v[160:163], v[192:195], v[90:93]
	v_mfma_f32_16x16x32_bf16 v[82:85], v[168:171], v[192:195], v[82:85]
	v_mfma_f32_16x16x32_bf16 v[74:77], v[160:163], v[206:209], v[74:77]
	v_mfma_f32_16x16x32_bf16 v[66:69], v[168:171], v[206:209], v[66:69]
	v_mfma_f32_16x16x32_bf16 v[122:125], v[164:167], v[180:183], v[122:125]
	v_mfma_f32_16x16x32_bf16 v[114:117], v[172:175], v[180:183], v[114:117]
	v_mfma_f32_16x16x32_bf16 v[106:109], v[164:167], v[188:191], v[106:109]
	v_mfma_f32_16x16x32_bf16 v[98:101], v[172:175], v[188:191], v[98:101]
	v_mfma_f32_16x16x32_bf16 v[90:93], v[164:167], v[202:205], v[90:93]
	v_mfma_f32_16x16x32_bf16 v[82:85], v[172:175], v[202:205], v[82:85]
	v_mfma_f32_16x16x32_bf16 v[74:77], v[164:167], v[210:213], v[74:77]
	v_mfma_f32_16x16x32_bf16 v[66:69], v[172:175], v[210:213], v[66:69]
	s_barrier
	s_setprio 0
	s_add_i32 s1, s70, s26
	v_lshl_add_u64 v[214:215], s[8:9], 0, v[196:197]
	s_mov_b32 m0, s1
	ds_read_b128 v[176:179], v143 offset:16384
	ds_read_b128 v[180:183], v143 offset:17408
	ds_read_b128 v[184:187], v143 offset:18432
	ds_read_b128 v[188:191], v143 offset:19456
	ds_read_b128 v[192:195], v143 offset:20480
	ds_read_b128 v[202:205], v143 offset:21504
	ds_read_b128 v[206:209], v143 offset:22528
	ds_read_b128 v[210:213], v143 offset:23552
	global_load_lds_dwordx4 v[214:215], off
	s_add_i32 m0, s1, 0x2000
	s_add_u32 s70, s8, 0x80000
	v_lshl_add_u64 v[216:217], s[8:9], 0, v[130:131]
	s_addc_u32 s71, s9, 0
	s_add_i32 s0, s0, s26
	global_load_lds_dwordx4 v[216:217], off
	v_lshl_add_u64 v[218:219], s[70:71], 0, v[196:197]
	s_mov_b32 m0, s0
	v_lshl_add_u64 v[220:221], s[58:59], 0, v[132:133]
	global_load_lds_dwordx4 v[218:219], off
	v_lshl_add_u64 v[218:219], s[70:71], 0, v[130:131]
	s_add_i32 m0, s0, 0x2000
	s_nop 0
	global_load_lds_dwordx4 v[218:219], off
	v_lshl_add_u64 v[218:219], s[58:59], 0, v[134:135]
	s_mov_b32 m0, s27
	s_nop 0
	global_load_lds_dwordx4 v[218:219], off
	s_mov_b32 m0, s28
	s_nop 0
	global_load_lds_dwordx4 v[220:221], off
	s_waitcnt vmcnt(8) lgkmcnt(0)
	s_setprio 1
	s_barrier
	v_mfma_f32_16x16x32_bf16 v[62:65], v[144:147], v[176:179], v[62:65]
	v_mfma_f32_16x16x32_bf16 v[54:57], v[152:155], v[176:179], v[54:57]
	v_mfma_f32_16x16x32_bf16 v[46:49], v[144:147], v[184:187], v[46:49]
	v_mfma_f32_16x16x32_bf16 v[38:41], v[152:155], v[184:187], v[38:41]
	v_mfma_f32_16x16x32_bf16 v[30:33], v[144:147], v[192:195], v[30:33]
	v_mfma_f32_16x16x32_bf16 v[22:25], v[152:155], v[192:195], v[22:25]
	v_mfma_f32_16x16x32_bf16 v[14:17], v[144:147], v[206:209], v[14:17]
	v_mfma_f32_16x16x32_bf16 v[6:9], v[152:155], v[206:209], v[6:9]
	v_mfma_f32_16x16x32_bf16 v[62:65], v[148:151], v[180:183], v[62:65]
	v_mfma_f32_16x16x32_bf16 v[54:57], v[156:159], v[180:183], v[54:57]
	v_mfma_f32_16x16x32_bf16 v[46:49], v[148:151], v[188:191], v[46:49]
	v_mfma_f32_16x16x32_bf16 v[38:41], v[156:159], v[188:191], v[38:41]
	v_mfma_f32_16x16x32_bf16 v[30:33], v[148:151], v[202:205], v[30:33]
	v_mfma_f32_16x16x32_bf16 v[22:25], v[156:159], v[202:205], v[22:25]
	v_mfma_f32_16x16x32_bf16 v[14:17], v[148:151], v[210:213], v[14:17]
	v_mfma_f32_16x16x32_bf16 v[6:9], v[156:159], v[210:213], v[6:9]
	v_mfma_f32_16x16x32_bf16 v[58:61], v[160:163], v[176:179], v[58:61]
	v_mfma_f32_16x16x32_bf16 v[50:53], v[168:171], v[176:179], v[50:53]
	v_mfma_f32_16x16x32_bf16 v[42:45], v[160:163], v[184:187], v[42:45]
	v_mfma_f32_16x16x32_bf16 v[34:37], v[168:171], v[184:187], v[34:37]
	v_mfma_f32_16x16x32_bf16 v[26:29], v[160:163], v[192:195], v[26:29]
	v_mfma_f32_16x16x32_bf16 v[18:21], v[168:171], v[192:195], v[18:21]
	v_mfma_f32_16x16x32_bf16 v[10:13], v[160:163], v[206:209], v[10:13]
	v_mfma_f32_16x16x32_bf16 v[2:5], v[168:171], v[206:209], v[2:5]
	v_mfma_f32_16x16x32_bf16 v[58:61], v[164:167], v[180:183], v[58:61]
	v_mfma_f32_16x16x32_bf16 v[50:53], v[172:175], v[180:183], v[50:53]
	v_mfma_f32_16x16x32_bf16 v[42:45], v[164:167], v[188:191], v[42:45]
	v_mfma_f32_16x16x32_bf16 v[34:37], v[172:175], v[188:191], v[34:37]
	v_mfma_f32_16x16x32_bf16 v[26:29], v[164:167], v[202:205], v[26:29]
	v_mfma_f32_16x16x32_bf16 v[18:21], v[172:175], v[202:205], v[18:21]
	v_mfma_f32_16x16x32_bf16 v[10:13], v[164:167], v[210:213], v[10:13]
	v_mfma_f32_16x16x32_bf16 v[2:5], v[172:175], v[210:213], v[2:5]
	s_barrier
	s_setprio 0
	s_add_i32 s0, 0, 0x18000
	s_add_i32 s1, 0, 0x1c000
	v_add_u32_e32 v156, s0, v141
	v_add_u32_e32 v172, s1, v141
	ds_read_b128 v[144:147], v156
	ds_read_b128 v[148:151], v156 offset:1024
	ds_read_b128 v[152:155], v156 offset:2048
	ds_read_b128 v[156:159], v156 offset:3072
	ds_read_b128 v[160:163], v172
	ds_read_b128 v[164:167], v172 offset:1024
	ds_read_b128 v[168:171], v172 offset:2048
	ds_read_b128 v[172:175], v172 offset:3072
	s_add_u32 s58, s58, 0x80000
	s_addc_u32 s59, s59, 0
	s_mov_b32 m0, s29
	v_lshl_add_u64 v[222:223], s[58:59], 0, v[134:135]
	ds_read_b128 v[176:179], v143 offset:32768
	ds_read_b128 v[180:183], v143 offset:33792
	ds_read_b128 v[184:187], v143 offset:34816
	ds_read_b128 v[188:191], v143 offset:35840
	ds_read_b128 v[192:195], v143 offset:36864
	ds_read_b128 v[202:205], v143 offset:37888
	ds_read_b128 v[206:209], v143 offset:38912
	ds_read_b128 v[210:213], v143 offset:39936
	global_load_lds_dwordx4 v[222:223], off
	v_lshl_add_u64 v[222:223], s[58:59], 0, v[132:133]
	s_mov_b32 m0, s30
	s_nop 0
	global_load_lds_dwordx4 v[222:223], off
	s_waitcnt vmcnt(8) lgkmcnt(0)
	s_setprio 1
	s_barrier
	v_mfma_f32_16x16x32_bf16 v[126:129], v[144:147], v[176:179], v[126:129]
	v_mfma_f32_16x16x32_bf16 v[118:121], v[152:155], v[176:179], v[118:121]
	v_mfma_f32_16x16x32_bf16 v[110:113], v[144:147], v[184:187], v[110:113]
	v_mfma_f32_16x16x32_bf16 v[102:105], v[152:155], v[184:187], v[102:105]
	v_mfma_f32_16x16x32_bf16 v[94:97], v[144:147], v[192:195], v[94:97]
	v_mfma_f32_16x16x32_bf16 v[86:89], v[152:155], v[192:195], v[86:89]
	v_mfma_f32_16x16x32_bf16 v[78:81], v[144:147], v[206:209], v[78:81]
	v_mfma_f32_16x16x32_bf16 v[70:73], v[152:155], v[206:209], v[70:73]
	v_mfma_f32_16x16x32_bf16 v[126:129], v[148:151], v[180:183], v[126:129]
	v_mfma_f32_16x16x32_bf16 v[118:121], v[156:159], v[180:183], v[118:121]
	v_mfma_f32_16x16x32_bf16 v[110:113], v[148:151], v[188:191], v[110:113]
	v_mfma_f32_16x16x32_bf16 v[102:105], v[156:159], v[188:191], v[102:105]
	v_mfma_f32_16x16x32_bf16 v[94:97], v[148:151], v[202:205], v[94:97]
	v_mfma_f32_16x16x32_bf16 v[86:89], v[156:159], v[202:205], v[86:89]
	v_mfma_f32_16x16x32_bf16 v[78:81], v[148:151], v[210:213], v[78:81]
	v_mfma_f32_16x16x32_bf16 v[70:73], v[156:159], v[210:213], v[70:73]
	v_mfma_f32_16x16x32_bf16 v[122:125], v[160:163], v[176:179], v[122:125]
	v_mfma_f32_16x16x32_bf16 v[114:117], v[168:171], v[176:179], v[114:117]
	v_mfma_f32_16x16x32_bf16 v[106:109], v[160:163], v[184:187], v[106:109]
	v_mfma_f32_16x16x32_bf16 v[98:101], v[168:171], v[184:187], v[98:101]
	v_mfma_f32_16x16x32_bf16 v[90:93], v[160:163], v[192:195], v[90:93]
	v_mfma_f32_16x16x32_bf16 v[82:85], v[168:171], v[192:195], v[82:85]
	v_mfma_f32_16x16x32_bf16 v[74:77], v[160:163], v[206:209], v[74:77]
	v_mfma_f32_16x16x32_bf16 v[66:69], v[168:171], v[206:209], v[66:69]
	v_mfma_f32_16x16x32_bf16 v[122:125], v[164:167], v[180:183], v[122:125]
	v_mfma_f32_16x16x32_bf16 v[114:117], v[172:175], v[180:183], v[114:117]
	v_mfma_f32_16x16x32_bf16 v[106:109], v[164:167], v[188:191], v[106:109]
	v_mfma_f32_16x16x32_bf16 v[98:101], v[172:175], v[188:191], v[98:101]
	v_mfma_f32_16x16x32_bf16 v[90:93], v[164:167], v[202:205], v[90:93]
	v_mfma_f32_16x16x32_bf16 v[82:85], v[172:175], v[202:205], v[82:85]
	v_mfma_f32_16x16x32_bf16 v[74:77], v[164:167], v[210:213], v[74:77]
	v_mfma_f32_16x16x32_bf16 v[66:69], v[172:175], v[210:213], v[66:69]
	s_barrier
	s_setprio 0
	s_add_i32 s0, s0, s26
	v_lshl_add_u64 v[214:215], v[214:215], 0, s[16:17]
	s_mov_b32 m0, s0
	ds_read_b128 v[176:179], v143 offset:49152
	ds_read_b128 v[180:183], v143 offset:50176
	ds_read_b128 v[184:187], v143 offset:51200
	ds_read_b128 v[188:191], v143 offset:52224
	ds_read_b128 v[192:195], v143 offset:53248
	ds_read_b128 v[202:205], v143 offset:54272
	ds_read_b128 v[206:209], v143 offset:55296
	ds_read_b128 v[210:213], v143 offset:56320
	global_load_lds_dwordx4 v[214:215], off
	s_add_i32 m0, s0, 0x2000
	s_add_u32 s8, s8, 0x80080
	v_lshl_add_u64 v[214:215], v[216:217], 0, s[16:17]
	s_addc_u32 s9, s9, 0
	s_add_i32 s0, s1, s26
	global_load_lds_dwordx4 v[214:215], off
	v_lshl_add_u64 v[214:215], s[8:9], 0, v[196:197]
	s_mov_b32 m0, s0
	s_nop 0
	global_load_lds_dwordx4 v[214:215], off
	v_lshl_add_u64 v[214:215], s[8:9], 0, v[130:131]
	s_add_i32 m0, s0, 0x2000
	s_nop 0
	global_load_lds_dwordx4 v[214:215], off
	v_lshl_add_u64 v[214:215], v[218:219], 0, s[16:17]
	s_mov_b32 m0, s31
	s_nop 0
	global_load_lds_dwordx4 v[214:215], off
	v_lshl_add_u64 v[214:215], v[220:221], 0, s[16:17]
	s_mov_b32 m0, s34
	s_nop 0
	global_load_lds_dwordx4 v[214:215], off
	s_waitcnt vmcnt(8) lgkmcnt(0)
	s_setprio 1
	s_barrier
	v_mfma_f32_16x16x32_bf16 v[62:65], v[144:147], v[176:179], v[62:65]
	v_mfma_f32_16x16x32_bf16 v[54:57], v[152:155], v[176:179], v[54:57]
	v_mfma_f32_16x16x32_bf16 v[46:49], v[144:147], v[184:187], v[46:49]
	v_mfma_f32_16x16x32_bf16 v[38:41], v[152:155], v[184:187], v[38:41]
	v_mfma_f32_16x16x32_bf16 v[30:33], v[144:147], v[192:195], v[30:33]
	v_mfma_f32_16x16x32_bf16 v[22:25], v[152:155], v[192:195], v[22:25]
	v_mfma_f32_16x16x32_bf16 v[14:17], v[144:147], v[206:209], v[14:17]
	v_mfma_f32_16x16x32_bf16 v[6:9], v[152:155], v[206:209], v[6:9]
	v_mfma_f32_16x16x32_bf16 v[62:65], v[148:151], v[180:183], v[62:65]
	v_mfma_f32_16x16x32_bf16 v[54:57], v[156:159], v[180:183], v[54:57]
	v_mfma_f32_16x16x32_bf16 v[46:49], v[148:151], v[188:191], v[46:49]
	v_mfma_f32_16x16x32_bf16 v[38:41], v[156:159], v[188:191], v[38:41]
	v_mfma_f32_16x16x32_bf16 v[30:33], v[148:151], v[202:205], v[30:33]
	v_mfma_f32_16x16x32_bf16 v[22:25], v[156:159], v[202:205], v[22:25]
	v_mfma_f32_16x16x32_bf16 v[14:17], v[148:151], v[210:213], v[14:17]
	v_mfma_f32_16x16x32_bf16 v[6:9], v[156:159], v[210:213], v[6:9]
	v_mfma_f32_16x16x32_bf16 v[58:61], v[160:163], v[176:179], v[58:61]
	v_mfma_f32_16x16x32_bf16 v[50:53], v[168:171], v[176:179], v[50:53]
	v_mfma_f32_16x16x32_bf16 v[42:45], v[160:163], v[184:187], v[42:45]
	v_mfma_f32_16x16x32_bf16 v[34:37], v[168:171], v[184:187], v[34:37]
	v_mfma_f32_16x16x32_bf16 v[26:29], v[160:163], v[192:195], v[26:29]
	v_mfma_f32_16x16x32_bf16 v[18:21], v[168:171], v[192:195], v[18:21]
	v_mfma_f32_16x16x32_bf16 v[10:13], v[160:163], v[206:209], v[10:13]
	v_mfma_f32_16x16x32_bf16 v[2:5], v[168:171], v[206:209], v[2:5]
	v_mfma_f32_16x16x32_bf16 v[58:61], v[164:167], v[180:183], v[58:61]
	v_mfma_f32_16x16x32_bf16 v[50:53], v[172:175], v[180:183], v[50:53]
	v_mfma_f32_16x16x32_bf16 v[42:45], v[164:167], v[188:191], v[42:45]
	v_mfma_f32_16x16x32_bf16 v[34:37], v[172:175], v[188:191], v[34:37]
	v_mfma_f32_16x16x32_bf16 v[26:29], v[164:167], v[202:205], v[26:29]
	v_mfma_f32_16x16x32_bf16 v[18:21], v[172:175], v[202:205], v[18:21]
	v_mfma_f32_16x16x32_bf16 v[10:13], v[164:167], v[210:213], v[10:13]
	v_mfma_f32_16x16x32_bf16 v[2:5], v[172:175], v[210:213], v[2:5]
	s_barrier
	s_setprio 0
	s_add_u32 s67, s67, 0x100
	s_addc_u32 s68, s68, 0
	s_add_u32 s52, s52, 0x100
	s_addc_u32 s53, s53, 0
	s_cmp_ge_i32 s69, s62
	s_mov_b32 s8, s69
	s_cbranch_scc0 .LBB0_904
	s_and_b64 vcc, exec, s[38:39]
	s_cbranch_vccz .LBB0_907
	s_barrier

.LBB0_987:
	s_add_i32 s72, s50, 2
	s_add_u32 s8, s48, 0x100
	s_addc_u32 s9, s49, 0
	s_add_i32 s0, 0, 0x10000
	s_cmp_eq_u32 s41, s50
	s_cselect_b32 s53, s45, s9
	s_cselect_b32 s52, s44, s8
	s_cselect_b32 s51, s47, s71
	s_cselect_b32 s50, s46, s70
	s_add_i32 s1, 0, 0x14000
	v_add_u32_e32 v142, s0, v188
	v_add_u32_e32 v172, s1, v188
	ds_read_b128 v[130:133], v142
	ds_read_b128 v[134:137], v142 offset:1024
	ds_read_b128 v[138:141], v142 offset:2048
	ds_read_b128 v[142:145], v142 offset:3072
	ds_read_b128 v[146:149], v172
	ds_read_b128 v[164:167], v172 offset:1024
	ds_read_b128 v[168:171], v172 offset:2048
	ds_read_b128 v[172:175], v172 offset:3072
	v_lshl_add_u64 v[194:195], s[48:49], 0, v[162:163]
	s_add_i32 m0, s27, 0xc000
	ds_read_b128 v[176:179], v189
	ds_read_b128 v[180:183], v189 offset:1024
	ds_read_b128 v[184:187], v189 offset:2048
	ds_read_b128 v[190:193], v189 offset:3072
	ds_read_b128 v[202:205], v189 offset:4096
	ds_read_b128 v[206:209], v189 offset:5120
	ds_read_b128 v[210:213], v189 offset:6144
	ds_read_b128 v[214:217], v189 offset:7168
	global_load_lds_dwordx4 v[194:195], off
	v_lshl_add_u64 v[194:195], s[48:49], 0, v[160:161]
	s_add_i32 m0, s27, 0xe000
	s_nop 0
	global_load_lds_dwordx4 v[194:195], off
	s_waitcnt vmcnt(8) lgkmcnt(0)
	s_setprio 1
	s_barrier
	v_mfma_f32_16x16x32_bf16 v[126:129], v[130:133], v[176:179], v[126:129]
	v_mfma_f32_16x16x32_bf16 v[122:125], v[138:141], v[176:179], v[122:125]
	v_mfma_f32_16x16x32_bf16 v[110:113], v[130:133], v[184:187], v[110:113]
	v_mfma_f32_16x16x32_bf16 v[106:109], v[138:141], v[184:187], v[106:109]
	v_mfma_f32_16x16x32_bf16 v[98:101], v[130:133], v[202:205], v[98:101]
	v_mfma_f32_16x16x32_bf16 v[90:93], v[138:141], v[202:205], v[90:93]
	v_mfma_f32_16x16x32_bf16 v[82:85], v[130:133], v[210:213], v[82:85]
	v_mfma_f32_16x16x32_bf16 v[74:77], v[138:141], v[210:213], v[74:77]
	v_mfma_f32_16x16x32_bf16 v[126:129], v[134:137], v[180:183], v[126:129]
	v_mfma_f32_16x16x32_bf16 v[122:125], v[142:145], v[180:183], v[122:125]
	v_mfma_f32_16x16x32_bf16 v[110:113], v[134:137], v[190:193], v[110:113]
	v_mfma_f32_16x16x32_bf16 v[106:109], v[142:145], v[190:193], v[106:109]
	v_mfma_f32_16x16x32_bf16 v[98:101], v[134:137], v[206:209], v[98:101]
	v_mfma_f32_16x16x32_bf16 v[90:93], v[142:145], v[206:209], v[90:93]
	v_mfma_f32_16x16x32_bf16 v[82:85], v[134:137], v[214:217], v[82:85]
	v_mfma_f32_16x16x32_bf16 v[74:77], v[142:145], v[214:217], v[74:77]
	v_mfma_f32_16x16x32_bf16 v[118:121], v[146:149], v[176:179], v[118:121]
	v_mfma_f32_16x16x32_bf16 v[114:117], v[168:171], v[176:179], v[114:117]
	v_mfma_f32_16x16x32_bf16 v[102:105], v[146:149], v[184:187], v[102:105]
	v_mfma_f32_16x16x32_bf16 v[94:97], v[168:171], v[184:187], v[94:97]
	v_mfma_f32_16x16x32_bf16 v[86:89], v[146:149], v[202:205], v[86:89]
	v_mfma_f32_16x16x32_bf16 v[78:81], v[168:171], v[202:205], v[78:81]
	v_mfma_f32_16x16x32_bf16 v[70:73], v[146:149], v[210:213], v[70:73]
	v_mfma_f32_16x16x32_bf16 v[66:69], v[168:171], v[210:213], v[66:69]
	v_mfma_f32_16x16x32_bf16 v[118:121], v[164:167], v[180:183], v[118:121]
	v_mfma_f32_16x16x32_bf16 v[114:117], v[172:175], v[180:183], v[114:117]
	v_mfma_f32_16x16x32_bf16 v[102:105], v[164:167], v[190:193], v[102:105]
	v_mfma_f32_16x16x32_bf16 v[94:97], v[172:175], v[190:193], v[94:97]
	v_mfma_f32_16x16x32_bf16 v[86:89], v[164:167], v[206:209], v[86:89]
	v_mfma_f32_16x16x32_bf16 v[78:81], v[172:175], v[206:209], v[78:81]
	v_mfma_f32_16x16x32_bf16 v[70:73], v[164:167], v[214:217], v[70:73]
	v_mfma_f32_16x16x32_bf16 v[66:69], v[172:175], v[214:217], v[66:69]
	s_barrier
	s_setprio 0
	s_add_i32 s0, s0, s26
	v_lshl_add_u64 v[194:195], s[50:51], 0, v[196:197]
	s_mov_b32 m0, s0
	ds_read_b128 v[176:179], v189 offset:16384
	ds_read_b128 v[180:183], v189 offset:17408
	ds_read_b128 v[184:187], v189 offset:18432
	ds_read_b128 v[190:193], v189 offset:19456
	ds_read_b128 v[202:205], v189 offset:20480
	ds_read_b128 v[206:209], v189 offset:21504
	ds_read_b128 v[210:213], v189 offset:22528
	ds_read_b128 v[214:217], v189 offset:23552
	global_load_lds_dwordx4 v[194:195], off
	s_add_i32 m0, s0, 0x2000
	s_add_u32 s48, s50, 0x158000
	v_lshl_add_u64 v[218:219], s[50:51], 0, v[154:155]
	s_addc_u32 s49, s51, 0
	s_add_i32 s0, s1, s26
	global_load_lds_dwordx4 v[218:219], off
	v_lshl_add_u64 v[220:221], s[48:49], 0, v[196:197]
	s_mov_b32 m0, s0
	v_lshl_add_u64 v[222:223], s[52:53], 0, v[152:153]
	global_load_lds_dwordx4 v[220:221], off
	v_lshl_add_u64 v[220:221], s[48:49], 0, v[154:155]
	s_add_i32 m0, s0, 0x2000
	s_nop 0
	global_load_lds_dwordx4 v[220:221], off
	v_lshl_add_u64 v[220:221], s[52:53], 0, v[150:151]
	s_mov_b32 m0, s27
	s_nop 0
	global_load_lds_dwordx4 v[220:221], off
	s_mov_b32 m0, s28
	s_nop 0
	global_load_lds_dwordx4 v[222:223], off
	s_waitcnt vmcnt(8) lgkmcnt(0)
	s_setprio 1
	s_barrier
	v_mfma_f32_16x16x32_bf16 v[62:65], v[130:133], v[176:179], v[62:65]
	v_mfma_f32_16x16x32_bf16 v[58:61], v[138:141], v[176:179], v[58:61]
	v_mfma_f32_16x16x32_bf16 v[50:53], v[130:133], v[184:187], v[50:53]
	v_mfma_f32_16x16x32_bf16 v[42:45], v[138:141], v[184:187], v[42:45]
	v_mfma_f32_16x16x32_bf16 v[34:37], v[130:133], v[202:205], v[34:37]
	v_mfma_f32_16x16x32_bf16 v[26:29], v[138:141], v[202:205], v[26:29]
	v_mfma_f32_16x16x32_bf16 v[18:21], v[130:133], v[210:213], v[18:21]
	v_mfma_f32_16x16x32_bf16 v[10:13], v[138:141], v[210:213], v[10:13]
	v_mfma_f32_16x16x32_bf16 v[62:65], v[134:137], v[180:183], v[62:65]
	v_mfma_f32_16x16x32_bf16 v[58:61], v[142:145], v[180:183], v[58:61]
	v_mfma_f32_16x16x32_bf16 v[50:53], v[134:137], v[190:193], v[50:53]
	v_mfma_f32_16x16x32_bf16 v[42:45], v[142:145], v[190:193], v[42:45]
	v_mfma_f32_16x16x32_bf16 v[34:37], v[134:137], v[206:209], v[34:37]
	v_mfma_f32_16x16x32_bf16 v[26:29], v[142:145], v[206:209], v[26:29]
	v_mfma_f32_16x16x32_bf16 v[18:21], v[134:137], v[214:217], v[18:21]
	v_mfma_f32_16x16x32_bf16 v[10:13], v[142:145], v[214:217], v[10:13]
	v_mfma_f32_16x16x32_bf16 v[54:57], v[146:149], v[176:179], v[54:57]
	v_mfma_f32_16x16x32_bf16 v[46:49], v[168:171], v[176:179], v[46:49]
	v_mfma_f32_16x16x32_bf16 v[38:41], v[146:149], v[184:187], v[38:41]
	v_mfma_f32_16x16x32_bf16 v[30:33], v[168:171], v[184:187], v[30:33]
	v_mfma_f32_16x16x32_bf16 v[22:25], v[146:149], v[202:205], v[22:25]
	v_mfma_f32_16x16x32_bf16 v[14:17], v[168:171], v[202:205], v[14:17]
	v_mfma_f32_16x16x32_bf16 v[6:9], v[146:149], v[210:213], v[6:9]
	v_mfma_f32_16x16x32_bf16 v[2:5], v[168:171], v[210:213], v[2:5]
	v_mfma_f32_16x16x32_bf16 v[54:57], v[164:167], v[180:183], v[54:57]
	v_mfma_f32_16x16x32_bf16 v[46:49], v[172:175], v[180:183], v[46:49]
	v_mfma_f32_16x16x32_bf16 v[38:41], v[164:167], v[190:193], v[38:41]
	v_mfma_f32_16x16x32_bf16 v[30:33], v[172:175], v[190:193], v[30:33]
	v_mfma_f32_16x16x32_bf16 v[22:25], v[164:167], v[206:209], v[22:25]
	v_mfma_f32_16x16x32_bf16 v[14:17], v[172:175], v[206:209], v[14:17]
	v_mfma_f32_16x16x32_bf16 v[6:9], v[164:167], v[214:217], v[6:9]
	v_mfma_f32_16x16x32_bf16 v[2:5], v[172:175], v[214:217], v[2:5]
	s_barrier
	s_setprio 0
	s_add_i32 s0, 0, 0x18000
	s_add_i32 s1, 0, 0x1c000
	v_add_u32_e32 v142, s0, v188
	v_add_u32_e32 v172, s1, v188
	ds_read_b128 v[130:133], v142
	ds_read_b128 v[134:137], v142 offset:1024
	ds_read_b128 v[138:141], v142 offset:2048
	ds_read_b128 v[142:145], v142 offset:3072
	ds_read_b128 v[146:149], v172
	ds_read_b128 v[164:167], v172 offset:1024
	ds_read_b128 v[168:171], v172 offset:2048
	ds_read_b128 v[172:175], v172 offset:3072
	s_add_u32 s48, s52, 0x158000
	s_addc_u32 s49, s53, 0
	s_mov_b32 m0, s29
	v_lshl_add_u64 v[224:225], s[48:49], 0, v[150:151]
	ds_read_b128 v[176:179], v189 offset:32768
	ds_read_b128 v[180:183], v189 offset:33792
	ds_read_b128 v[184:187], v189 offset:34816
	ds_read_b128 v[190:193], v189 offset:35840
	ds_read_b128 v[202:205], v189 offset:36864
	ds_read_b128 v[206:209], v189 offset:37888
	ds_read_b128 v[210:213], v189 offset:38912
	ds_read_b128 v[214:217], v189 offset:39936
	global_load_lds_dwordx4 v[224:225], off
	v_lshl_add_u64 v[224:225], s[48:49], 0, v[152:153]
	s_mov_b32 m0, s30
	s_nop 0
	global_load_lds_dwordx4 v[224:225], off
	s_waitcnt vmcnt(8) lgkmcnt(0)
	s_setprio 1
	s_barrier
	v_mfma_f32_16x16x32_bf16 v[126:129], v[130:133], v[176:179], v[126:129]
	v_mfma_f32_16x16x32_bf16 v[122:125], v[138:141], v[176:179], v[122:125]
	v_mfma_f32_16x16x32_bf16 v[110:113], v[130:133], v[184:187], v[110:113]
	v_mfma_f32_16x16x32_bf16 v[106:109], v[138:141], v[184:187], v[106:109]
	v_mfma_f32_16x16x32_bf16 v[98:101], v[130:133], v[202:205], v[98:101]
	v_mfma_f32_16x16x32_bf16 v[90:93], v[138:141], v[202:205], v[90:93]
	v_mfma_f32_16x16x32_bf16 v[82:85], v[130:133], v[210:213], v[82:85]
	v_mfma_f32_16x16x32_bf16 v[74:77], v[138:141], v[210:213], v[74:77]
	v_mfma_f32_16x16x32_bf16 v[126:129], v[134:137], v[180:183], v[126:129]
	v_mfma_f32_16x16x32_bf16 v[122:125], v[142:145], v[180:183], v[122:125]
	v_mfma_f32_16x16x32_bf16 v[110:113], v[134:137], v[190:193], v[110:113]
	v_mfma_f32_16x16x32_bf16 v[106:109], v[142:145], v[190:193], v[106:109]
	v_mfma_f32_16x16x32_bf16 v[98:101], v[134:137], v[206:209], v[98:101]
	v_mfma_f32_16x16x32_bf16 v[90:93], v[142:145], v[206:209], v[90:93]
	v_mfma_f32_16x16x32_bf16 v[82:85], v[134:137], v[214:217], v[82:85]
	v_mfma_f32_16x16x32_bf16 v[74:77], v[142:145], v[214:217], v[74:77]
	v_mfma_f32_16x16x32_bf16 v[118:121], v[146:149], v[176:179], v[118:121]
	v_mfma_f32_16x16x32_bf16 v[114:117], v[168:171], v[176:179], v[114:117]
	v_mfma_f32_16x16x32_bf16 v[102:105], v[146:149], v[184:187], v[102:105]
	v_mfma_f32_16x16x32_bf16 v[94:97], v[168:171], v[184:187], v[94:97]
	v_mfma_f32_16x16x32_bf16 v[86:89], v[146:149], v[202:205], v[86:89]
	v_mfma_f32_16x16x32_bf16 v[78:81], v[168:171], v[202:205], v[78:81]
	v_mfma_f32_16x16x32_bf16 v[70:73], v[146:149], v[210:213], v[70:73]
	v_mfma_f32_16x16x32_bf16 v[66:69], v[168:171], v[210:213], v[66:69]
	v_mfma_f32_16x16x32_bf16 v[118:121], v[164:167], v[180:183], v[118:121]
	v_mfma_f32_16x16x32_bf16 v[114:117], v[172:175], v[180:183], v[114:117]
	v_mfma_f32_16x16x32_bf16 v[102:105], v[164:167], v[190:193], v[102:105]
	v_mfma_f32_16x16x32_bf16 v[94:97], v[172:175], v[190:193], v[94:97]
	v_mfma_f32_16x16x32_bf16 v[86:89], v[164:167], v[206:209], v[86:89]
	v_mfma_f32_16x16x32_bf16 v[78:81], v[172:175], v[206:209], v[78:81]
	v_mfma_f32_16x16x32_bf16 v[70:73], v[164:167], v[214:217], v[70:73]
	v_mfma_f32_16x16x32_bf16 v[66:69], v[172:175], v[214:217], v[66:69]
	s_barrier
	s_setprio 0
	s_add_i32 s0, s0, s26
	v_lshl_add_u64 v[194:195], v[194:195], 0, s[16:17]
	s_mov_b32 m0, s0
	ds_read_b128 v[176:179], v189 offset:49152
	ds_read_b128 v[180:183], v189 offset:50176
	ds_read_b128 v[184:187], v189 offset:51200
	ds_read_b128 v[190:193], v189 offset:52224
	ds_read_b128 v[202:205], v189 offset:53248
	ds_read_b128 v[206:209], v189 offset:54272
	ds_read_b128 v[210:213], v189 offset:55296
	ds_read_b128 v[214:217], v189 offset:56320
	global_load_lds_dwordx4 v[194:195], off
	s_add_i32 m0, s0, 0x2000
	s_add_u32 s48, s50, 0x158080
	v_lshl_add_u64 v[194:195], v[218:219], 0, s[16:17]
	s_addc_u32 s49, s51, 0
	s_add_i32 s0, s1, s26
	global_load_lds_dwordx4 v[194:195], off
	v_lshl_add_u64 v[194:195], s[48:49], 0, v[196:197]
	s_mov_b32 m0, s0
	s_nop 0
	global_load_lds_dwordx4 v[194:195], off
	v_lshl_add_u64 v[194:195], s[48:49], 0, v[154:155]
	s_add_i32 m0, s0, 0x2000
	s_nop 0
	global_load_lds_dwordx4 v[194:195], off
	v_lshl_add_u64 v[194:195], v[220:221], 0, s[16:17]
	s_mov_b32 m0, s35
	s_nop 0
	global_load_lds_dwordx4 v[194:195], off
	v_lshl_add_u64 v[194:195], v[222:223], 0, s[16:17]
	s_mov_b32 m0, s58
	s_nop 0
	global_load_lds_dwordx4 v[194:195], off
	s_waitcnt vmcnt(8) lgkmcnt(0)
	s_setprio 1
	s_barrier
	v_mfma_f32_16x16x32_bf16 v[62:65], v[130:133], v[176:179], v[62:65]
	v_mfma_f32_16x16x32_bf16 v[58:61], v[138:141], v[176:179], v[58:61]
	v_mfma_f32_16x16x32_bf16 v[50:53], v[130:133], v[184:187], v[50:53]
	v_mfma_f32_16x16x32_bf16 v[42:45], v[138:141], v[184:187], v[42:45]
	v_mfma_f32_16x16x32_bf16 v[34:37], v[130:133], v[202:205], v[34:37]
	v_mfma_f32_16x16x32_bf16 v[26:29], v[138:141], v[202:205], v[26:29]
	v_mfma_f32_16x16x32_bf16 v[18:21], v[130:133], v[210:213], v[18:21]
	v_mfma_f32_16x16x32_bf16 v[10:13], v[138:141], v[210:213], v[10:13]
	v_mfma_f32_16x16x32_bf16 v[62:65], v[134:137], v[180:183], v[62:65]
	v_mfma_f32_16x16x32_bf16 v[58:61], v[142:145], v[180:183], v[58:61]
	v_mfma_f32_16x16x32_bf16 v[50:53], v[134:137], v[190:193], v[50:53]
	v_mfma_f32_16x16x32_bf16 v[42:45], v[142:145], v[190:193], v[42:45]
	v_mfma_f32_16x16x32_bf16 v[34:37], v[134:137], v[206:209], v[34:37]
	v_mfma_f32_16x16x32_bf16 v[26:29], v[142:145], v[206:209], v[26:29]
	v_mfma_f32_16x16x32_bf16 v[18:21], v[134:137], v[214:217], v[18:21]
	v_mfma_f32_16x16x32_bf16 v[10:13], v[142:145], v[214:217], v[10:13]
	v_mfma_f32_16x16x32_bf16 v[54:57], v[146:149], v[176:179], v[54:57]
	v_mfma_f32_16x16x32_bf16 v[46:49], v[168:171], v[176:179], v[46:49]
	v_mfma_f32_16x16x32_bf16 v[38:41], v[146:149], v[184:187], v[38:41]
	v_mfma_f32_16x16x32_bf16 v[30:33], v[168:171], v[184:187], v[30:33]
	v_mfma_f32_16x16x32_bf16 v[22:25], v[146:149], v[202:205], v[22:25]
	v_mfma_f32_16x16x32_bf16 v[14:17], v[168:171], v[202:205], v[14:17]
	v_mfma_f32_16x16x32_bf16 v[6:9], v[146:149], v[210:213], v[6:9]
	v_mfma_f32_16x16x32_bf16 v[2:5], v[168:171], v[210:213], v[2:5]
	v_mfma_f32_16x16x32_bf16 v[54:57], v[164:167], v[180:183], v[54:57]
	v_mfma_f32_16x16x32_bf16 v[46:49], v[172:175], v[180:183], v[46:49]
	v_mfma_f32_16x16x32_bf16 v[38:41], v[164:167], v[190:193], v[38:41]
	v_mfma_f32_16x16x32_bf16 v[30:33], v[172:175], v[190:193], v[30:33]
	v_mfma_f32_16x16x32_bf16 v[22:25], v[164:167], v[206:209], v[22:25]
	v_mfma_f32_16x16x32_bf16 v[14:17], v[172:175], v[206:209], v[14:17]
	v_mfma_f32_16x16x32_bf16 v[6:9], v[164:167], v[214:217], v[6:9]
	v_mfma_f32_16x16x32_bf16 v[2:5], v[172:175], v[214:217], v[2:5]
	s_barrier
	s_setprio 0
	s_add_u32 s70, s70, 0x100
	s_addc_u32 s71, s71, 0
	s_cmp_ge_i32 s72, s69
	s_mov_b64 s[48:49], s[8:9]
	s_mov_b32 s50, s72
	s_cbranch_scc0 .LBB0_987
	s_and_b64 vcc, exec, s[38:39]
	s_cbranch_vccz .LBB0_990
	s_barrier

.LBB0_1135:
	s_add_i32 s71, s8, 2
	s_add_u32 s0, s58, 0xfff80080
	s_addc_u32 s1, s59, -1
	s_add_i32 s72, 0, 0x10000
	s_cmp_eq_u32 s68, s8
	s_cselect_b32 s63, s43, s1
	s_cselect_b32 s62, s47, s0
	v_add_u32_e32 v146, s72, v149
	s_cselect_b32 s9, s45, s70
	s_cselect_b32 s8, s67, s69
	s_add_i32 s0, 0, 0x14000
	ds_read_b128 v[142:145], v146
	ds_read_b128 v[152:155], v146 offset:1024
	ds_read_b128 v[156:159], v146 offset:2048
	ds_read_b128 v[160:163], v146 offset:3072
	v_add_u32_e32 v146, s0, v149
	ds_read_b128 v[164:167], v146
	ds_read_b128 v[168:171], v146 offset:1024
	ds_read_b128 v[172:175], v146 offset:2048
	ds_read_b128 v[176:179], v146 offset:3072
	v_lshl_add_u64 v[146:147], s[58:59], 0, v[140:141]
	s_add_i32 m0, s27, 0xc000
	ds_read_b128 v[180:183], v151
	ds_read_b128 v[184:187], v151 offset:1024
	ds_read_b128 v[188:191], v151 offset:2048
	ds_read_b128 v[192:195], v151 offset:3072
	ds_read_b128 v[202:205], v151 offset:4096
	ds_read_b128 v[206:209], v151 offset:5120
	ds_read_b128 v[210:213], v151 offset:6144
	ds_read_b128 v[214:217], v151 offset:7168
	global_load_lds_dwordx4 v[146:147], off
	v_lshl_add_u64 v[146:147], s[58:59], 0, v[138:139]
	s_add_i32 m0, s27, 0xe000
	s_nop 0
	global_load_lds_dwordx4 v[146:147], off
	s_waitcnt vmcnt(8) lgkmcnt(0)
	s_setprio 1
	s_barrier
	v_mfma_f32_16x16x32_bf16 v[126:129], v[142:145], v[180:183], v[126:129]
	v_mfma_f32_16x16x32_bf16 v[122:125], v[156:159], v[180:183], v[122:125]
	v_mfma_f32_16x16x32_bf16 v[118:121], v[142:145], v[188:191], v[118:121]
	v_mfma_f32_16x16x32_bf16 v[110:113], v[156:159], v[188:191], v[110:113]
	v_mfma_f32_16x16x32_bf16 v[102:105], v[142:145], v[202:205], v[102:105]
	v_mfma_f32_16x16x32_bf16 v[94:97], v[156:159], v[202:205], v[94:97]
	v_mfma_f32_16x16x32_bf16 v[86:89], v[142:145], v[210:213], v[86:89]
	v_mfma_f32_16x16x32_bf16 v[78:81], v[156:159], v[210:213], v[78:81]
	v_mfma_f32_16x16x32_bf16 v[126:129], v[152:155], v[184:187], v[126:129]
	v_mfma_f32_16x16x32_bf16 v[122:125], v[160:163], v[184:187], v[122:125]
	v_mfma_f32_16x16x32_bf16 v[118:121], v[152:155], v[192:195], v[118:121]
	v_mfma_f32_16x16x32_bf16 v[110:113], v[160:163], v[192:195], v[110:113]
	v_mfma_f32_16x16x32_bf16 v[102:105], v[152:155], v[206:209], v[102:105]
	v_mfma_f32_16x16x32_bf16 v[94:97], v[160:163], v[206:209], v[94:97]
	v_mfma_f32_16x16x32_bf16 v[86:89], v[152:155], v[214:217], v[86:89]
	v_mfma_f32_16x16x32_bf16 v[78:81], v[160:163], v[214:217], v[78:81]
	v_mfma_f32_16x16x32_bf16 v[114:117], v[164:167], v[180:183], v[114:117]
	v_mfma_f32_16x16x32_bf16 v[106:109], v[172:175], v[180:183], v[106:109]
	v_mfma_f32_16x16x32_bf16 v[98:101], v[164:167], v[188:191], v[98:101]
	v_mfma_f32_16x16x32_bf16 v[90:93], v[172:175], v[188:191], v[90:93]
	v_mfma_f32_16x16x32_bf16 v[82:85], v[164:167], v[202:205], v[82:85]
	v_mfma_f32_16x16x32_bf16 v[74:77], v[172:175], v[202:205], v[74:77]
	v_mfma_f32_16x16x32_bf16 v[70:73], v[164:167], v[210:213], v[70:73]
	v_mfma_f32_16x16x32_bf16 v[66:69], v[172:175], v[210:213], v[66:69]
	v_mfma_f32_16x16x32_bf16 v[114:117], v[168:171], v[184:187], v[114:117]
	v_mfma_f32_16x16x32_bf16 v[106:109], v[176:179], v[184:187], v[106:109]
	v_mfma_f32_16x16x32_bf16 v[98:101], v[168:171], v[192:195], v[98:101]
	v_mfma_f32_16x16x32_bf16 v[90:93], v[176:179], v[192:195], v[90:93]
	v_mfma_f32_16x16x32_bf16 v[82:85], v[168:171], v[206:209], v[82:85]
	v_mfma_f32_16x16x32_bf16 v[74:77], v[176:179], v[206:209], v[74:77]
	v_mfma_f32_16x16x32_bf16 v[70:73], v[168:171], v[214:217], v[70:73]
	v_mfma_f32_16x16x32_bf16 v[66:69], v[176:179], v[214:217], v[66:69]
	s_barrier
	s_setprio 0
	s_add_i32 s1, s72, s26
	v_lshl_add_u64 v[146:147], s[8:9], 0, v[196:197]
	s_mov_b32 m0, s1
	ds_read_b128 v[180:183], v151 offset:16384
	ds_read_b128 v[184:187], v151 offset:17408
	ds_read_b128 v[188:191], v151 offset:18432
	ds_read_b128 v[192:195], v151 offset:19456
	ds_read_b128 v[202:205], v151 offset:20480
	ds_read_b128 v[206:209], v151 offset:21504
	ds_read_b128 v[210:213], v151 offset:22528
	ds_read_b128 v[214:217], v151 offset:23552
	global_load_lds_dwordx4 v[146:147], off
	s_add_i32 m0, s1, 0x2000
	s_add_u32 s72, s8, 0x80000
	v_lshl_add_u64 v[218:219], s[8:9], 0, v[130:131]
	s_addc_u32 s73, s9, 0
	s_add_i32 s0, s0, s26
	global_load_lds_dwordx4 v[218:219], off
	v_lshl_add_u64 v[220:221], s[72:73], 0, v[196:197]
	s_mov_b32 m0, s0
	v_lshl_add_u64 v[222:223], s[62:63], 0, v[132:133]
	global_load_lds_dwordx4 v[220:221], off
	v_lshl_add_u64 v[220:221], s[72:73], 0, v[130:131]
	s_add_i32 m0, s0, 0x2000
	s_nop 0
	global_load_lds_dwordx4 v[220:221], off
	v_lshl_add_u64 v[220:221], s[62:63], 0, v[134:135]
	s_mov_b32 m0, s27
	s_nop 0
	global_load_lds_dwordx4 v[220:221], off
	s_mov_b32 m0, s28
	s_nop 0
	global_load_lds_dwordx4 v[222:223], off
	s_waitcnt vmcnt(8) lgkmcnt(0)
	s_setprio 1
	s_barrier
	v_mfma_f32_16x16x32_bf16 v[62:65], v[142:145], v[180:183], v[62:65]
	v_mfma_f32_16x16x32_bf16 v[58:61], v[156:159], v[180:183], v[58:61]
	v_mfma_f32_16x16x32_bf16 v[54:57], v[142:145], v[188:191], v[54:57]
	v_mfma_f32_16x16x32_bf16 v[46:49], v[156:159], v[188:191], v[46:49]
	v_mfma_f32_16x16x32_bf16 v[38:41], v[142:145], v[202:205], v[38:41]
	v_mfma_f32_16x16x32_bf16 v[30:33], v[156:159], v[202:205], v[30:33]
	v_mfma_f32_16x16x32_bf16 v[22:25], v[142:145], v[210:213], v[22:25]
	v_mfma_f32_16x16x32_bf16 v[14:17], v[156:159], v[210:213], v[14:17]
	v_mfma_f32_16x16x32_bf16 v[62:65], v[152:155], v[184:187], v[62:65]
	v_mfma_f32_16x16x32_bf16 v[58:61], v[160:163], v[184:187], v[58:61]
	v_mfma_f32_16x16x32_bf16 v[54:57], v[152:155], v[192:195], v[54:57]
	v_mfma_f32_16x16x32_bf16 v[46:49], v[160:163], v[192:195], v[46:49]
	v_mfma_f32_16x16x32_bf16 v[38:41], v[152:155], v[206:209], v[38:41]
	v_mfma_f32_16x16x32_bf16 v[30:33], v[160:163], v[206:209], v[30:33]
	v_mfma_f32_16x16x32_bf16 v[22:25], v[152:155], v[214:217], v[22:25]
	v_mfma_f32_16x16x32_bf16 v[14:17], v[160:163], v[214:217], v[14:17]
	v_mfma_f32_16x16x32_bf16 v[50:53], v[164:167], v[180:183], v[50:53]
	v_mfma_f32_16x16x32_bf16 v[42:45], v[172:175], v[180:183], v[42:45]
	v_mfma_f32_16x16x32_bf16 v[34:37], v[164:167], v[188:191], v[34:37]
	v_mfma_f32_16x16x32_bf16 v[26:29], v[172:175], v[188:191], v[26:29]
	v_mfma_f32_16x16x32_bf16 v[18:21], v[164:167], v[202:205], v[18:21]
	v_mfma_f32_16x16x32_bf16 v[10:13], v[172:175], v[202:205], v[10:13]
	v_mfma_f32_16x16x32_bf16 v[6:9], v[164:167], v[210:213], v[6:9]
	v_mfma_f32_16x16x32_bf16 v[2:5], v[172:175], v[210:213], v[2:5]
	v_mfma_f32_16x16x32_bf16 v[50:53], v[168:171], v[184:187], v[50:53]
	v_mfma_f32_16x16x32_bf16 v[42:45], v[176:179], v[184:187], v[42:45]
	v_mfma_f32_16x16x32_bf16 v[34:37], v[168:171], v[192:195], v[34:37]
	v_mfma_f32_16x16x32_bf16 v[26:29], v[176:179], v[192:195], v[26:29]
	v_mfma_f32_16x16x32_bf16 v[18:21], v[168:171], v[206:209], v[18:21]
	v_mfma_f32_16x16x32_bf16 v[10:13], v[176:179], v[206:209], v[10:13]
	v_mfma_f32_16x16x32_bf16 v[6:9], v[168:171], v[214:217], v[6:9]
	v_mfma_f32_16x16x32_bf16 v[2:5], v[176:179], v[214:217], v[2:5]
	s_barrier
	s_setprio 0
	s_add_i32 s0, 0, 0x18000
	s_add_i32 s1, 0, 0x1c000
	v_add_u32_e32 v160, s0, v149
	v_add_u32_e32 v176, s1, v149
	ds_read_b128 v[142:145], v160
	ds_read_b128 v[152:155], v160 offset:1024
	ds_read_b128 v[156:159], v160 offset:2048
	ds_read_b128 v[160:163], v160 offset:3072
	ds_read_b128 v[164:167], v176
	ds_read_b128 v[168:171], v176 offset:1024
	ds_read_b128 v[172:175], v176 offset:2048
	ds_read_b128 v[176:179], v176 offset:3072
	s_add_u32 s62, s62, 0x80000
	s_addc_u32 s63, s63, 0
	s_mov_b32 m0, s29
	v_lshl_add_u64 v[224:225], s[62:63], 0, v[134:135]
	ds_read_b128 v[180:183], v151 offset:32768
	ds_read_b128 v[184:187], v151 offset:33792
	ds_read_b128 v[188:191], v151 offset:34816
	ds_read_b128 v[192:195], v151 offset:35840
	ds_read_b128 v[202:205], v151 offset:36864
	ds_read_b128 v[206:209], v151 offset:37888
	ds_read_b128 v[210:213], v151 offset:38912
	ds_read_b128 v[214:217], v151 offset:39936
	global_load_lds_dwordx4 v[224:225], off
	v_lshl_add_u64 v[224:225], s[62:63], 0, v[132:133]
	s_mov_b32 m0, s30
	s_nop 0
	global_load_lds_dwordx4 v[224:225], off
	s_waitcnt vmcnt(8) lgkmcnt(0)
	s_setprio 1
	s_barrier
	v_mfma_f32_16x16x32_bf16 v[126:129], v[142:145], v[180:183], v[126:129]
	v_mfma_f32_16x16x32_bf16 v[122:125], v[156:159], v[180:183], v[122:125]
	v_mfma_f32_16x16x32_bf16 v[118:121], v[142:145], v[188:191], v[118:121]
	v_mfma_f32_16x16x32_bf16 v[110:113], v[156:159], v[188:191], v[110:113]
	v_mfma_f32_16x16x32_bf16 v[102:105], v[142:145], v[202:205], v[102:105]
	v_mfma_f32_16x16x32_bf16 v[94:97], v[156:159], v[202:205], v[94:97]
	v_mfma_f32_16x16x32_bf16 v[86:89], v[142:145], v[210:213], v[86:89]
	v_mfma_f32_16x16x32_bf16 v[78:81], v[156:159], v[210:213], v[78:81]
	v_mfma_f32_16x16x32_bf16 v[126:129], v[152:155], v[184:187], v[126:129]
	v_mfma_f32_16x16x32_bf16 v[122:125], v[160:163], v[184:187], v[122:125]
	v_mfma_f32_16x16x32_bf16 v[118:121], v[152:155], v[192:195], v[118:121]
	v_mfma_f32_16x16x32_bf16 v[110:113], v[160:163], v[192:195], v[110:113]
	v_mfma_f32_16x16x32_bf16 v[102:105], v[152:155], v[206:209], v[102:105]
	v_mfma_f32_16x16x32_bf16 v[94:97], v[160:163], v[206:209], v[94:97]
	v_mfma_f32_16x16x32_bf16 v[86:89], v[152:155], v[214:217], v[86:89]
	v_mfma_f32_16x16x32_bf16 v[78:81], v[160:163], v[214:217], v[78:81]
	v_mfma_f32_16x16x32_bf16 v[114:117], v[164:167], v[180:183], v[114:117]
	v_mfma_f32_16x16x32_bf16 v[106:109], v[172:175], v[180:183], v[106:109]
	v_mfma_f32_16x16x32_bf16 v[98:101], v[164:167], v[188:191], v[98:101]
	v_mfma_f32_16x16x32_bf16 v[90:93], v[172:175], v[188:191], v[90:93]
	v_mfma_f32_16x16x32_bf16 v[82:85], v[164:167], v[202:205], v[82:85]
	v_mfma_f32_16x16x32_bf16 v[74:77], v[172:175], v[202:205], v[74:77]
	v_mfma_f32_16x16x32_bf16 v[70:73], v[164:167], v[210:213], v[70:73]
	v_mfma_f32_16x16x32_bf16 v[66:69], v[172:175], v[210:213], v[66:69]
	v_mfma_f32_16x16x32_bf16 v[114:117], v[168:171], v[184:187], v[114:117]
	v_mfma_f32_16x16x32_bf16 v[106:109], v[176:179], v[184:187], v[106:109]
	v_mfma_f32_16x16x32_bf16 v[98:101], v[168:171], v[192:195], v[98:101]
	v_mfma_f32_16x16x32_bf16 v[90:93], v[176:179], v[192:195], v[90:93]
	v_mfma_f32_16x16x32_bf16 v[82:85], v[168:171], v[206:209], v[82:85]
	v_mfma_f32_16x16x32_bf16 v[74:77], v[176:179], v[206:209], v[74:77]
	v_mfma_f32_16x16x32_bf16 v[70:73], v[168:171], v[214:217], v[70:73]
	v_mfma_f32_16x16x32_bf16 v[66:69], v[176:179], v[214:217], v[66:69]
	s_barrier
	s_setprio 0
	s_add_i32 s0, s0, s26
	v_lshl_add_u64 v[146:147], v[146:147], 0, s[16:17]
	s_mov_b32 m0, s0
	ds_read_b128 v[180:183], v151 offset:49152
	ds_read_b128 v[184:187], v151 offset:50176
	ds_read_b128 v[188:191], v151 offset:51200
	ds_read_b128 v[192:195], v151 offset:52224
	ds_read_b128 v[202:205], v151 offset:53248
	ds_read_b128 v[206:209], v151 offset:54272
	ds_read_b128 v[210:213], v151 offset:55296
	ds_read_b128 v[214:217], v151 offset:56320
	global_load_lds_dwordx4 v[146:147], off
	s_add_i32 m0, s0, 0x2000
	s_add_u32 s8, s8, 0x80080
	v_lshl_add_u64 v[146:147], v[218:219], 0, s[16:17]
	s_addc_u32 s9, s9, 0
	s_add_i32 s0, s1, s26
	global_load_lds_dwordx4 v[146:147], off
	v_lshl_add_u64 v[146:147], s[8:9], 0, v[196:197]
	s_mov_b32 m0, s0
	s_nop 0
	global_load_lds_dwordx4 v[146:147], off
	v_lshl_add_u64 v[146:147], s[8:9], 0, v[130:131]
	s_add_i32 m0, s0, 0x2000
	s_nop 0
	global_load_lds_dwordx4 v[146:147], off
	v_lshl_add_u64 v[146:147], v[220:221], 0, s[16:17]
	s_mov_b32 m0, s31
	s_nop 0
	global_load_lds_dwordx4 v[146:147], off
	v_lshl_add_u64 v[146:147], v[222:223], 0, s[16:17]
	s_mov_b32 m0, s34
	s_nop 0
	global_load_lds_dwordx4 v[146:147], off
	s_waitcnt vmcnt(8) lgkmcnt(0)
	s_setprio 1
	s_barrier
	v_mfma_f32_16x16x32_bf16 v[62:65], v[142:145], v[180:183], v[62:65]
	v_mfma_f32_16x16x32_bf16 v[58:61], v[156:159], v[180:183], v[58:61]
	v_mfma_f32_16x16x32_bf16 v[54:57], v[142:145], v[188:191], v[54:57]
	v_mfma_f32_16x16x32_bf16 v[46:49], v[156:159], v[188:191], v[46:49]
	v_mfma_f32_16x16x32_bf16 v[38:41], v[142:145], v[202:205], v[38:41]
	v_mfma_f32_16x16x32_bf16 v[30:33], v[156:159], v[202:205], v[30:33]
	v_mfma_f32_16x16x32_bf16 v[22:25], v[142:145], v[210:213], v[22:25]
	v_mfma_f32_16x16x32_bf16 v[14:17], v[156:159], v[210:213], v[14:17]
	v_mfma_f32_16x16x32_bf16 v[62:65], v[152:155], v[184:187], v[62:65]
	v_mfma_f32_16x16x32_bf16 v[58:61], v[160:163], v[184:187], v[58:61]
	v_mfma_f32_16x16x32_bf16 v[54:57], v[152:155], v[192:195], v[54:57]
	v_mfma_f32_16x16x32_bf16 v[46:49], v[160:163], v[192:195], v[46:49]
	v_mfma_f32_16x16x32_bf16 v[38:41], v[152:155], v[206:209], v[38:41]
	v_mfma_f32_16x16x32_bf16 v[30:33], v[160:163], v[206:209], v[30:33]
	v_mfma_f32_16x16x32_bf16 v[22:25], v[152:155], v[214:217], v[22:25]
	v_mfma_f32_16x16x32_bf16 v[14:17], v[160:163], v[214:217], v[14:17]
	v_mfma_f32_16x16x32_bf16 v[50:53], v[164:167], v[180:183], v[50:53]
	v_mfma_f32_16x16x32_bf16 v[42:45], v[172:175], v[180:183], v[42:45]
	v_mfma_f32_16x16x32_bf16 v[34:37], v[164:167], v[188:191], v[34:37]
	v_mfma_f32_16x16x32_bf16 v[26:29], v[172:175], v[188:191], v[26:29]
	v_mfma_f32_16x16x32_bf16 v[18:21], v[164:167], v[202:205], v[18:21]
	v_mfma_f32_16x16x32_bf16 v[10:13], v[172:175], v[202:205], v[10:13]
	v_mfma_f32_16x16x32_bf16 v[6:9], v[164:167], v[210:213], v[6:9]
	v_mfma_f32_16x16x32_bf16 v[2:5], v[172:175], v[210:213], v[2:5]
	v_mfma_f32_16x16x32_bf16 v[50:53], v[168:171], v[184:187], v[50:53]
	v_mfma_f32_16x16x32_bf16 v[42:45], v[176:179], v[184:187], v[42:45]
	v_mfma_f32_16x16x32_bf16 v[34:37], v[168:171], v[192:195], v[34:37]
	v_mfma_f32_16x16x32_bf16 v[26:29], v[176:179], v[192:195], v[26:29]
	v_mfma_f32_16x16x32_bf16 v[18:21], v[168:171], v[206:209], v[18:21]
	v_mfma_f32_16x16x32_bf16 v[10:13], v[176:179], v[206:209], v[10:13]
	v_mfma_f32_16x16x32_bf16 v[6:9], v[168:171], v[214:217], v[6:9]
	v_mfma_f32_16x16x32_bf16 v[2:5], v[176:179], v[214:217], v[2:5]
	s_barrier
	s_setprio 0
	s_add_u32 s69, s69, 0x100
	s_addc_u32 s70, s70, 0
	s_add_u32 s58, s58, 0x100
	s_addc_u32 s59, s59, 0
	s_cmp_ge_i32 s71, s64
	s_mov_b32 s8, s71
	s_cbranch_scc0 .LBB0_1135
	s_and_b64 vcc, exec, s[38:39]
	s_cbranch_vccz .LBB0_1138
	s_barrier

.LBB0_2239:
	s_add_i32 s73, s8, 2
	s_add_u32 s0, s44, 0xfff00080
	s_addc_u32 s1, s45, -1
	s_add_i32 s77, 0, 0x10000
	s_cmp_eq_u32 s70, s8
	s_cselect_b32 s67, s51, s1
	s_cselect_b32 s66, s53, s0
	s_cselect_b32 s9, s49, s72
	s_cselect_b32 s8, s69, s71
	s_add_i32 s78, 0, 0x14000
	v_add_u32_e32 v142, s77, v244
	v_add_u32_e32 v158, s78, v244
	ds_read_b128 v[130:133], v142
	ds_read_b128 v[134:137], v142 offset:1024
	ds_read_b128 v[138:141], v142 offset:2048
	ds_read_b128 v[142:145], v142 offset:3072
	ds_read_b128 v[146:149], v158
	ds_read_b128 v[150:153], v158 offset:1024
	ds_read_b128 v[154:157], v158 offset:2048
	ds_read_b128 v[158:161], v158 offset:3072
	v_lshl_add_u64 v[194:195], s[44:45], 0, v[210:211]
	s_add_i32 m0, s3, 0xc000
	ds_read_b128 v[162:165], v246
	ds_read_b128 v[166:169], v246 offset:1024
	ds_read_b128 v[170:173], v246 offset:2048
	ds_read_b128 v[174:177], v246 offset:3072
	ds_read_b128 v[178:181], v246 offset:4096
	ds_read_b128 v[182:185], v246 offset:5120
	ds_read_b128 v[186:189], v246 offset:6144
	ds_read_b128 v[190:193], v246 offset:7168
	global_load_lds_dwordx4 v[194:195], off
	v_lshl_add_u64 v[194:195], s[44:45], 0, v[208:209]
	s_add_i32 m0, s3, 0xe000
	s_nop 0
	global_load_lds_dwordx4 v[194:195], off
	s_waitcnt vmcnt(8) lgkmcnt(0)
	s_setprio 1
	s_barrier
	v_mfma_f32_16x16x32_bf16 v[126:129], v[130:133], v[162:165], v[126:129]
	v_mfma_f32_16x16x32_bf16 v[122:125], v[138:141], v[162:165], v[122:125]
	v_mfma_f32_16x16x32_bf16 v[110:113], v[130:133], v[170:173], v[110:113]
	v_mfma_f32_16x16x32_bf16 v[106:109], v[138:141], v[170:173], v[106:109]
	v_mfma_f32_16x16x32_bf16 v[94:97], v[130:133], v[178:181], v[94:97]
	v_mfma_f32_16x16x32_bf16 v[90:93], v[138:141], v[178:181], v[90:93]
	v_mfma_f32_16x16x32_bf16 v[78:81], v[130:133], v[186:189], v[78:81]
	v_mfma_f32_16x16x32_bf16 v[74:77], v[138:141], v[186:189], v[74:77]
	v_mfma_f32_16x16x32_bf16 v[126:129], v[134:137], v[166:169], v[126:129]
	v_mfma_f32_16x16x32_bf16 v[122:125], v[142:145], v[166:169], v[122:125]
	v_mfma_f32_16x16x32_bf16 v[110:113], v[134:137], v[174:177], v[110:113]
	v_mfma_f32_16x16x32_bf16 v[106:109], v[142:145], v[174:177], v[106:109]
	v_mfma_f32_16x16x32_bf16 v[94:97], v[134:137], v[182:185], v[94:97]
	v_mfma_f32_16x16x32_bf16 v[90:93], v[142:145], v[182:185], v[90:93]
	v_mfma_f32_16x16x32_bf16 v[78:81], v[134:137], v[190:193], v[78:81]
	v_mfma_f32_16x16x32_bf16 v[74:77], v[142:145], v[190:193], v[74:77]
	v_mfma_f32_16x16x32_bf16 v[118:121], v[146:149], v[162:165], v[118:121]
	v_mfma_f32_16x16x32_bf16 v[114:117], v[154:157], v[162:165], v[114:117]
	v_mfma_f32_16x16x32_bf16 v[102:105], v[146:149], v[170:173], v[102:105]
	v_mfma_f32_16x16x32_bf16 v[98:101], v[154:157], v[170:173], v[98:101]
	v_mfma_f32_16x16x32_bf16 v[86:89], v[146:149], v[178:181], v[86:89]
	v_mfma_f32_16x16x32_bf16 v[82:85], v[154:157], v[178:181], v[82:85]
	v_mfma_f32_16x16x32_bf16 v[70:73], v[146:149], v[186:189], v[70:73]
	v_mfma_f32_16x16x32_bf16 v[66:69], v[154:157], v[186:189], v[66:69]
	v_mfma_f32_16x16x32_bf16 v[118:121], v[150:153], v[166:169], v[118:121]
	v_mfma_f32_16x16x32_bf16 v[114:117], v[158:161], v[166:169], v[114:117]
	v_mfma_f32_16x16x32_bf16 v[102:105], v[150:153], v[174:177], v[102:105]
	v_mfma_f32_16x16x32_bf16 v[98:101], v[158:161], v[174:177], v[98:101]
	v_mfma_f32_16x16x32_bf16 v[86:89], v[150:153], v[182:185], v[86:89]
	v_mfma_f32_16x16x32_bf16 v[82:85], v[158:161], v[182:185], v[82:85]
	v_mfma_f32_16x16x32_bf16 v[70:73], v[150:153], v[190:193], v[70:73]
	v_mfma_f32_16x16x32_bf16 v[66:69], v[158:161], v[190:193], v[66:69]
	s_barrier
	s_setprio 0
	s_add_i32 s0, s77, s2
	v_lshl_add_u64 v[194:195], s[8:9], 0, v[196:197]
	s_mov_b32 m0, s0
	ds_read_b128 v[162:165], v246 offset:16384
	ds_read_b128 v[166:169], v246 offset:17408
	ds_read_b128 v[170:173], v246 offset:18432
	ds_read_b128 v[174:177], v246 offset:19456
	ds_read_b128 v[178:181], v246 offset:20480
	ds_read_b128 v[182:185], v246 offset:21504
	ds_read_b128 v[186:189], v246 offset:22528
	ds_read_b128 v[190:193], v246 offset:23552
	global_load_lds_dwordx4 v[194:195], off
	s_add_i32 m0, s0, 0x2000
	s_add_u32 s0, s8, 0x100000
	v_lshl_add_u64 v[212:213], s[8:9], 0, v[202:203]
	s_addc_u32 s1, s9, 0
	s_add_i32 s77, s78, s2
	global_load_lds_dwordx4 v[212:213], off
	v_lshl_add_u64 v[214:215], s[0:1], 0, v[196:197]
	s_mov_b32 m0, s77
	v_lshl_add_u64 v[216:217], s[66:67], 0, v[204:205]
	global_load_lds_dwordx4 v[214:215], off
	v_lshl_add_u64 v[214:215], s[0:1], 0, v[202:203]
	s_add_i32 m0, s77, 0x2000
	s_nop 0
	global_load_lds_dwordx4 v[214:215], off
	v_lshl_add_u64 v[214:215], s[66:67], 0, v[206:207]
	s_mov_b32 m0, s3
	s_nop 0
	global_load_lds_dwordx4 v[214:215], off
	s_mov_b32 m0, s10
	s_nop 0
	global_load_lds_dwordx4 v[216:217], off
	s_waitcnt vmcnt(8) lgkmcnt(0)
	s_setprio 1
	s_barrier
	v_mfma_f32_16x16x32_bf16 v[62:65], v[130:133], v[162:165], v[62:65]
	v_mfma_f32_16x16x32_bf16 v[58:61], v[138:141], v[162:165], v[58:61]
	v_mfma_f32_16x16x32_bf16 v[46:49], v[130:133], v[170:173], v[46:49]
	v_mfma_f32_16x16x32_bf16 v[42:45], v[138:141], v[170:173], v[42:45]
	v_mfma_f32_16x16x32_bf16 v[30:33], v[130:133], v[178:181], v[30:33]
	v_mfma_f32_16x16x32_bf16 v[26:29], v[138:141], v[178:181], v[26:29]
	v_mfma_f32_16x16x32_bf16 v[14:17], v[130:133], v[186:189], v[14:17]
	v_mfma_f32_16x16x32_bf16 v[10:13], v[138:141], v[186:189], v[10:13]
	v_mfma_f32_16x16x32_bf16 v[62:65], v[134:137], v[166:169], v[62:65]
	v_mfma_f32_16x16x32_bf16 v[58:61], v[142:145], v[166:169], v[58:61]
	v_mfma_f32_16x16x32_bf16 v[46:49], v[134:137], v[174:177], v[46:49]
	v_mfma_f32_16x16x32_bf16 v[42:45], v[142:145], v[174:177], v[42:45]
	v_mfma_f32_16x16x32_bf16 v[30:33], v[134:137], v[182:185], v[30:33]
	v_mfma_f32_16x16x32_bf16 v[26:29], v[142:145], v[182:185], v[26:29]
	v_mfma_f32_16x16x32_bf16 v[14:17], v[134:137], v[190:193], v[14:17]
	v_mfma_f32_16x16x32_bf16 v[10:13], v[142:145], v[190:193], v[10:13]
	v_mfma_f32_16x16x32_bf16 v[54:57], v[146:149], v[162:165], v[54:57]
	v_mfma_f32_16x16x32_bf16 v[50:53], v[154:157], v[162:165], v[50:53]
	v_mfma_f32_16x16x32_bf16 v[38:41], v[146:149], v[170:173], v[38:41]
	v_mfma_f32_16x16x32_bf16 v[34:37], v[154:157], v[170:173], v[34:37]
	v_mfma_f32_16x16x32_bf16 v[22:25], v[146:149], v[178:181], v[22:25]
	v_mfma_f32_16x16x32_bf16 v[18:21], v[154:157], v[178:181], v[18:21]
	v_mfma_f32_16x16x32_bf16 v[6:9], v[146:149], v[186:189], v[6:9]
	v_mfma_f32_16x16x32_bf16 v[2:5], v[154:157], v[186:189], v[2:5]
	v_mfma_f32_16x16x32_bf16 v[54:57], v[150:153], v[166:169], v[54:57]
	v_mfma_f32_16x16x32_bf16 v[50:53], v[158:161], v[166:169], v[50:53]
	v_mfma_f32_16x16x32_bf16 v[38:41], v[150:153], v[174:177], v[38:41]
	v_mfma_f32_16x16x32_bf16 v[34:37], v[158:161], v[174:177], v[34:37]
	v_mfma_f32_16x16x32_bf16 v[22:25], v[150:153], v[182:185], v[22:25]
	v_mfma_f32_16x16x32_bf16 v[18:21], v[158:161], v[182:185], v[18:21]
	v_mfma_f32_16x16x32_bf16 v[6:9], v[150:153], v[190:193], v[6:9]
	v_mfma_f32_16x16x32_bf16 v[2:5], v[158:161], v[190:193], v[2:5]
	s_barrier
	s_setprio 0
	s_add_i32 s77, 0, 0x18000
	s_add_i32 s78, 0, 0x1c000
	v_add_u32_e32 v142, s77, v244
	v_add_u32_e32 v158, s78, v244
	ds_read_b128 v[130:133], v142
	ds_read_b128 v[134:137], v142 offset:1024
	ds_read_b128 v[138:141], v142 offset:2048
	ds_read_b128 v[142:145], v142 offset:3072
	ds_read_b128 v[146:149], v158
	ds_read_b128 v[150:153], v158 offset:1024
	ds_read_b128 v[154:157], v158 offset:2048
	ds_read_b128 v[158:161], v158 offset:3072
	s_add_u32 s0, s66, 0x100000
	s_addc_u32 s1, s67, 0
	s_mov_b32 m0, s11
	v_lshl_add_u64 v[218:219], s[0:1], 0, v[206:207]
	ds_read_b128 v[162:165], v246 offset:32768
	ds_read_b128 v[166:169], v246 offset:33792
	ds_read_b128 v[170:173], v246 offset:34816
	ds_read_b128 v[174:177], v246 offset:35840
	ds_read_b128 v[178:181], v246 offset:36864
	ds_read_b128 v[182:185], v246 offset:37888
	ds_read_b128 v[186:189], v246 offset:38912
	ds_read_b128 v[190:193], v246 offset:39936
	global_load_lds_dwordx4 v[218:219], off
	v_lshl_add_u64 v[218:219], s[0:1], 0, v[204:205]
	s_mov_b32 m0, s26
	s_nop 0
	global_load_lds_dwordx4 v[218:219], off
	s_waitcnt vmcnt(8) lgkmcnt(0)
	s_setprio 1
	s_barrier
	v_mfma_f32_16x16x32_bf16 v[126:129], v[130:133], v[162:165], v[126:129]
	v_mfma_f32_16x16x32_bf16 v[122:125], v[138:141], v[162:165], v[122:125]
	v_mfma_f32_16x16x32_bf16 v[110:113], v[130:133], v[170:173], v[110:113]
	v_mfma_f32_16x16x32_bf16 v[106:109], v[138:141], v[170:173], v[106:109]
	v_mfma_f32_16x16x32_bf16 v[94:97], v[130:133], v[178:181], v[94:97]
	v_mfma_f32_16x16x32_bf16 v[90:93], v[138:141], v[178:181], v[90:93]
	v_mfma_f32_16x16x32_bf16 v[78:81], v[130:133], v[186:189], v[78:81]
	v_mfma_f32_16x16x32_bf16 v[74:77], v[138:141], v[186:189], v[74:77]
	v_mfma_f32_16x16x32_bf16 v[126:129], v[134:137], v[166:169], v[126:129]
	v_mfma_f32_16x16x32_bf16 v[122:125], v[142:145], v[166:169], v[122:125]
	v_mfma_f32_16x16x32_bf16 v[110:113], v[134:137], v[174:177], v[110:113]
	v_mfma_f32_16x16x32_bf16 v[106:109], v[142:145], v[174:177], v[106:109]
	v_mfma_f32_16x16x32_bf16 v[94:97], v[134:137], v[182:185], v[94:97]
	v_mfma_f32_16x16x32_bf16 v[90:93], v[142:145], v[182:185], v[90:93]
	v_mfma_f32_16x16x32_bf16 v[78:81], v[134:137], v[190:193], v[78:81]
	v_mfma_f32_16x16x32_bf16 v[74:77], v[142:145], v[190:193], v[74:77]
	v_mfma_f32_16x16x32_bf16 v[118:121], v[146:149], v[162:165], v[118:121]
	v_mfma_f32_16x16x32_bf16 v[114:117], v[154:157], v[162:165], v[114:117]
	v_mfma_f32_16x16x32_bf16 v[102:105], v[146:149], v[170:173], v[102:105]
	v_mfma_f32_16x16x32_bf16 v[98:101], v[154:157], v[170:173], v[98:101]
	v_mfma_f32_16x16x32_bf16 v[86:89], v[146:149], v[178:181], v[86:89]
	v_mfma_f32_16x16x32_bf16 v[82:85], v[154:157], v[178:181], v[82:85]
	v_mfma_f32_16x16x32_bf16 v[70:73], v[146:149], v[186:189], v[70:73]
	v_mfma_f32_16x16x32_bf16 v[66:69], v[154:157], v[186:189], v[66:69]
	v_mfma_f32_16x16x32_bf16 v[118:121], v[150:153], v[166:169], v[118:121]
	v_mfma_f32_16x16x32_bf16 v[114:117], v[158:161], v[166:169], v[114:117]
	v_mfma_f32_16x16x32_bf16 v[102:105], v[150:153], v[174:177], v[102:105]
	v_mfma_f32_16x16x32_bf16 v[98:101], v[158:161], v[174:177], v[98:101]
	v_mfma_f32_16x16x32_bf16 v[86:89], v[150:153], v[182:185], v[86:89]
	v_mfma_f32_16x16x32_bf16 v[82:85], v[158:161], v[182:185], v[82:85]
	v_mfma_f32_16x16x32_bf16 v[70:73], v[150:153], v[190:193], v[70:73]
	v_mfma_f32_16x16x32_bf16 v[66:69], v[158:161], v[190:193], v[66:69]
	s_barrier
	s_setprio 0
	s_add_i32 s0, s77, s2
	v_lshl_add_u64 v[194:195], v[194:195], 0, s[16:17]
	s_mov_b32 m0, s0
	ds_read_b128 v[162:165], v246 offset:49152
	ds_read_b128 v[166:169], v246 offset:50176
	ds_read_b128 v[170:173], v246 offset:51200
	ds_read_b128 v[174:177], v246 offset:52224
	ds_read_b128 v[178:181], v246 offset:53248
	ds_read_b128 v[182:185], v246 offset:54272
	ds_read_b128 v[186:189], v246 offset:55296
	ds_read_b128 v[190:193], v246 offset:56320
	global_load_lds_dwordx4 v[194:195], off
	s_add_i32 m0, s0, 0x2000
	s_add_u32 s0, s8, 0x100080
	v_lshl_add_u64 v[194:195], v[212:213], 0, s[16:17]
	s_addc_u32 s1, s9, 0
	s_add_i32 s8, s78, s2
	global_load_lds_dwordx4 v[194:195], off
	v_lshl_add_u64 v[194:195], s[0:1], 0, v[196:197]
	s_mov_b32 m0, s8
	s_nop 0
	global_load_lds_dwordx4 v[194:195], off
	v_lshl_add_u64 v[194:195], s[0:1], 0, v[202:203]
	s_add_i32 m0, s8, 0x2000
	s_nop 0
	global_load_lds_dwordx4 v[194:195], off
	v_lshl_add_u64 v[194:195], v[214:215], 0, s[16:17]
	s_mov_b32 m0, s27
	s_nop 0
	global_load_lds_dwordx4 v[194:195], off
	v_lshl_add_u64 v[194:195], v[216:217], 0, s[16:17]
	s_mov_b32 m0, s28
	s_nop 0
	global_load_lds_dwordx4 v[194:195], off
	s_waitcnt vmcnt(8) lgkmcnt(0)
	s_setprio 1
	s_barrier
	v_mfma_f32_16x16x32_bf16 v[62:65], v[130:133], v[162:165], v[62:65]
	v_mfma_f32_16x16x32_bf16 v[58:61], v[138:141], v[162:165], v[58:61]
	v_mfma_f32_16x16x32_bf16 v[46:49], v[130:133], v[170:173], v[46:49]
	v_mfma_f32_16x16x32_bf16 v[42:45], v[138:141], v[170:173], v[42:45]
	v_mfma_f32_16x16x32_bf16 v[30:33], v[130:133], v[178:181], v[30:33]
	v_mfma_f32_16x16x32_bf16 v[26:29], v[138:141], v[178:181], v[26:29]
	v_mfma_f32_16x16x32_bf16 v[14:17], v[130:133], v[186:189], v[14:17]
	v_mfma_f32_16x16x32_bf16 v[10:13], v[138:141], v[186:189], v[10:13]
	v_mfma_f32_16x16x32_bf16 v[62:65], v[134:137], v[166:169], v[62:65]
	v_mfma_f32_16x16x32_bf16 v[58:61], v[142:145], v[166:169], v[58:61]
	v_mfma_f32_16x16x32_bf16 v[46:49], v[134:137], v[174:177], v[46:49]
	v_mfma_f32_16x16x32_bf16 v[42:45], v[142:145], v[174:177], v[42:45]
	v_mfma_f32_16x16x32_bf16 v[30:33], v[134:137], v[182:185], v[30:33]
	v_mfma_f32_16x16x32_bf16 v[26:29], v[142:145], v[182:185], v[26:29]
	v_mfma_f32_16x16x32_bf16 v[14:17], v[134:137], v[190:193], v[14:17]
	v_mfma_f32_16x16x32_bf16 v[10:13], v[142:145], v[190:193], v[10:13]
	v_mfma_f32_16x16x32_bf16 v[54:57], v[146:149], v[162:165], v[54:57]
	v_mfma_f32_16x16x32_bf16 v[50:53], v[154:157], v[162:165], v[50:53]
	v_mfma_f32_16x16x32_bf16 v[38:41], v[146:149], v[170:173], v[38:41]
	v_mfma_f32_16x16x32_bf16 v[34:37], v[154:157], v[170:173], v[34:37]
	v_mfma_f32_16x16x32_bf16 v[22:25], v[146:149], v[178:181], v[22:25]
	v_mfma_f32_16x16x32_bf16 v[18:21], v[154:157], v[178:181], v[18:21]
	v_mfma_f32_16x16x32_bf16 v[6:9], v[146:149], v[186:189], v[6:9]
	v_mfma_f32_16x16x32_bf16 v[2:5], v[154:157], v[186:189], v[2:5]
	v_mfma_f32_16x16x32_bf16 v[54:57], v[150:153], v[166:169], v[54:57]
	v_mfma_f32_16x16x32_bf16 v[50:53], v[158:161], v[166:169], v[50:53]
	v_mfma_f32_16x16x32_bf16 v[38:41], v[150:153], v[174:177], v[38:41]
	v_mfma_f32_16x16x32_bf16 v[34:37], v[158:161], v[174:177], v[34:37]
	v_mfma_f32_16x16x32_bf16 v[22:25], v[150:153], v[182:185], v[22:25]
	v_mfma_f32_16x16x32_bf16 v[18:21], v[158:161], v[182:185], v[18:21]
	v_mfma_f32_16x16x32_bf16 v[6:9], v[150:153], v[190:193], v[6:9]
	v_mfma_f32_16x16x32_bf16 v[2:5], v[158:161], v[190:193], v[2:5]
	s_barrier
	s_setprio 0
	s_add_u32 s71, s71, 0x100
	s_addc_u32 s72, s72, 0
	s_add_u32 s44, s44, 0x100
	s_addc_u32 s45, s45, 0
	s_cmp_ge_i32 s73, s35
	s_mov_b32 s8, s73
	s_cbranch_scc0 .LBB0_2239
	s_and_b64 vcc, exec, s[46:47]
	s_cbranch_vccz .LBB0_2242
	s_barrier

.LBB0_2357:
	s_add_i32 s77, s8, 2
	s_add_u32 s0, s62, 0xfff80080
	s_addc_u32 s1, s63, -1
	s_add_i32 s78, 0, 0x10000
	s_cmp_eq_u32 s71, s8
	s_cselect_b32 s65, s41, s1
	s_cselect_b32 s64, s45, s0
	s_cselect_b32 s9, s43, s73
	s_cselect_b32 s8, s70, s72
	s_add_i32 s79, 0, 0x14000
	v_add_u32_e32 v142, s78, v188
	v_add_u32_e32 v158, s79, v188
	ds_read_b128 v[130:133], v142
	ds_read_b128 v[134:137], v142 offset:1024
	ds_read_b128 v[138:141], v142 offset:2048
	ds_read_b128 v[142:145], v142 offset:3072
	ds_read_b128 v[146:149], v158
	ds_read_b128 v[150:153], v158 offset:1024
	ds_read_b128 v[154:157], v158 offset:2048
	ds_read_b128 v[158:161], v158 offset:3072
	v_lshl_add_u64 v[194:195], s[62:63], 0, v[178:179]
	s_add_i32 m0, s27, 0xc000
	ds_read_b128 v[162:165], v189
	ds_read_b128 v[180:183], v189 offset:1024
	ds_read_b128 v[184:187], v189 offset:2048
	ds_read_b128 v[190:193], v189 offset:3072
	ds_read_b128 v[202:205], v189 offset:4096
	ds_read_b128 v[206:209], v189 offset:5120
	ds_read_b128 v[210:213], v189 offset:6144
	ds_read_b128 v[214:217], v189 offset:7168
	global_load_lds_dwordx4 v[194:195], off
	v_lshl_add_u64 v[194:195], s[62:63], 0, v[176:177]
	s_add_i32 m0, s27, 0xe000
	s_nop 0
	global_load_lds_dwordx4 v[194:195], off
	s_waitcnt vmcnt(8) lgkmcnt(0)
	s_setprio 1
	s_barrier
	v_mfma_f32_16x16x32_bf16 v[126:129], v[130:133], v[162:165], v[126:129]
	v_mfma_f32_16x16x32_bf16 v[122:125], v[138:141], v[162:165], v[122:125]
	v_mfma_f32_16x16x32_bf16 v[110:113], v[130:133], v[184:187], v[110:113]
	v_mfma_f32_16x16x32_bf16 v[106:109], v[138:141], v[184:187], v[106:109]
	v_mfma_f32_16x16x32_bf16 v[98:101], v[130:133], v[202:205], v[98:101]
	v_mfma_f32_16x16x32_bf16 v[90:93], v[138:141], v[202:205], v[90:93]
	v_mfma_f32_16x16x32_bf16 v[82:85], v[130:133], v[210:213], v[82:85]
	v_mfma_f32_16x16x32_bf16 v[74:77], v[138:141], v[210:213], v[74:77]
	v_mfma_f32_16x16x32_bf16 v[126:129], v[134:137], v[180:183], v[126:129]
	v_mfma_f32_16x16x32_bf16 v[122:125], v[142:145], v[180:183], v[122:125]
	v_mfma_f32_16x16x32_bf16 v[110:113], v[134:137], v[190:193], v[110:113]
	v_mfma_f32_16x16x32_bf16 v[106:109], v[142:145], v[190:193], v[106:109]
	v_mfma_f32_16x16x32_bf16 v[98:101], v[134:137], v[206:209], v[98:101]
	v_mfma_f32_16x16x32_bf16 v[90:93], v[142:145], v[206:209], v[90:93]
	v_mfma_f32_16x16x32_bf16 v[82:85], v[134:137], v[214:217], v[82:85]
	v_mfma_f32_16x16x32_bf16 v[74:77], v[142:145], v[214:217], v[74:77]
	v_mfma_f32_16x16x32_bf16 v[118:121], v[146:149], v[162:165], v[118:121]
	v_mfma_f32_16x16x32_bf16 v[114:117], v[154:157], v[162:165], v[114:117]
	v_mfma_f32_16x16x32_bf16 v[102:105], v[146:149], v[184:187], v[102:105]
	v_mfma_f32_16x16x32_bf16 v[94:97], v[154:157], v[184:187], v[94:97]
	v_mfma_f32_16x16x32_bf16 v[86:89], v[146:149], v[202:205], v[86:89]
	v_mfma_f32_16x16x32_bf16 v[78:81], v[154:157], v[202:205], v[78:81]
	v_mfma_f32_16x16x32_bf16 v[70:73], v[146:149], v[210:213], v[70:73]
	v_mfma_f32_16x16x32_bf16 v[66:69], v[154:157], v[210:213], v[66:69]
	v_mfma_f32_16x16x32_bf16 v[118:121], v[150:153], v[180:183], v[118:121]
	v_mfma_f32_16x16x32_bf16 v[114:117], v[158:161], v[180:183], v[114:117]
	v_mfma_f32_16x16x32_bf16 v[102:105], v[150:153], v[190:193], v[102:105]
	v_mfma_f32_16x16x32_bf16 v[94:97], v[158:161], v[190:193], v[94:97]
	v_mfma_f32_16x16x32_bf16 v[86:89], v[150:153], v[206:209], v[86:89]
	v_mfma_f32_16x16x32_bf16 v[78:81], v[158:161], v[206:209], v[78:81]
	v_mfma_f32_16x16x32_bf16 v[70:73], v[150:153], v[214:217], v[70:73]
	v_mfma_f32_16x16x32_bf16 v[66:69], v[158:161], v[214:217], v[66:69]
	s_barrier
	s_setprio 0
	s_add_i32 s0, s78, s26
	v_lshl_add_u64 v[194:195], s[8:9], 0, v[196:197]
	s_mov_b32 m0, s0
	ds_read_b128 v[162:165], v189 offset:16384
	ds_read_b128 v[180:183], v189 offset:17408
	ds_read_b128 v[184:187], v189 offset:18432
	ds_read_b128 v[190:193], v189 offset:19456
	ds_read_b128 v[202:205], v189 offset:20480
	ds_read_b128 v[206:209], v189 offset:21504
	ds_read_b128 v[210:213], v189 offset:22528
	ds_read_b128 v[214:217], v189 offset:23552
	global_load_lds_dwordx4 v[194:195], off
	s_add_i32 m0, s0, 0x2000
	s_add_u32 s0, s8, 0x80000
	v_lshl_add_u64 v[218:219], s[8:9], 0, v[170:171]
	s_addc_u32 s1, s9, 0
	s_add_i32 s78, s79, s26
	global_load_lds_dwordx4 v[218:219], off
	v_lshl_add_u64 v[220:221], s[0:1], 0, v[196:197]
	s_mov_b32 m0, s78
	v_lshl_add_u64 v[222:223], s[64:65], 0, v[168:169]
	global_load_lds_dwordx4 v[220:221], off
	v_lshl_add_u64 v[220:221], s[0:1], 0, v[170:171]
	s_add_i32 m0, s78, 0x2000
	s_nop 0
	global_load_lds_dwordx4 v[220:221], off
	v_lshl_add_u64 v[220:221], s[64:65], 0, v[166:167]
	s_mov_b32 m0, s27
	s_nop 0
	global_load_lds_dwordx4 v[220:221], off
	s_mov_b32 m0, s28
	s_nop 0
	global_load_lds_dwordx4 v[222:223], off
	s_waitcnt vmcnt(8) lgkmcnt(0)
	s_setprio 1
	s_barrier
	v_mfma_f32_16x16x32_bf16 v[62:65], v[130:133], v[162:165], v[62:65]
	v_mfma_f32_16x16x32_bf16 v[58:61], v[138:141], v[162:165], v[58:61]
	v_mfma_f32_16x16x32_bf16 v[50:53], v[130:133], v[184:187], v[50:53]
	v_mfma_f32_16x16x32_bf16 v[42:45], v[138:141], v[184:187], v[42:45]
	v_mfma_f32_16x16x32_bf16 v[34:37], v[130:133], v[202:205], v[34:37]
	v_mfma_f32_16x16x32_bf16 v[26:29], v[138:141], v[202:205], v[26:29]
	v_mfma_f32_16x16x32_bf16 v[18:21], v[130:133], v[210:213], v[18:21]
	v_mfma_f32_16x16x32_bf16 v[10:13], v[138:141], v[210:213], v[10:13]
	v_mfma_f32_16x16x32_bf16 v[62:65], v[134:137], v[180:183], v[62:65]
	v_mfma_f32_16x16x32_bf16 v[58:61], v[142:145], v[180:183], v[58:61]
	v_mfma_f32_16x16x32_bf16 v[50:53], v[134:137], v[190:193], v[50:53]
	v_mfma_f32_16x16x32_bf16 v[42:45], v[142:145], v[190:193], v[42:45]
	v_mfma_f32_16x16x32_bf16 v[34:37], v[134:137], v[206:209], v[34:37]
	v_mfma_f32_16x16x32_bf16 v[26:29], v[142:145], v[206:209], v[26:29]
	v_mfma_f32_16x16x32_bf16 v[18:21], v[134:137], v[214:217], v[18:21]
	v_mfma_f32_16x16x32_bf16 v[10:13], v[142:145], v[214:217], v[10:13]
	v_mfma_f32_16x16x32_bf16 v[54:57], v[146:149], v[162:165], v[54:57]
	v_mfma_f32_16x16x32_bf16 v[46:49], v[154:157], v[162:165], v[46:49]
	v_mfma_f32_16x16x32_bf16 v[38:41], v[146:149], v[184:187], v[38:41]
	v_mfma_f32_16x16x32_bf16 v[30:33], v[154:157], v[184:187], v[30:33]
	v_mfma_f32_16x16x32_bf16 v[22:25], v[146:149], v[202:205], v[22:25]
	v_mfma_f32_16x16x32_bf16 v[14:17], v[154:157], v[202:205], v[14:17]
	v_mfma_f32_16x16x32_bf16 v[6:9], v[146:149], v[210:213], v[6:9]
	v_mfma_f32_16x16x32_bf16 v[2:5], v[154:157], v[210:213], v[2:5]
	v_mfma_f32_16x16x32_bf16 v[54:57], v[150:153], v[180:183], v[54:57]
	v_mfma_f32_16x16x32_bf16 v[46:49], v[158:161], v[180:183], v[46:49]
	v_mfma_f32_16x16x32_bf16 v[38:41], v[150:153], v[190:193], v[38:41]
	v_mfma_f32_16x16x32_bf16 v[30:33], v[158:161], v[190:193], v[30:33]
	v_mfma_f32_16x16x32_bf16 v[22:25], v[150:153], v[206:209], v[22:25]
	v_mfma_f32_16x16x32_bf16 v[14:17], v[158:161], v[206:209], v[14:17]
	v_mfma_f32_16x16x32_bf16 v[6:9], v[150:153], v[214:217], v[6:9]
	v_mfma_f32_16x16x32_bf16 v[2:5], v[158:161], v[214:217], v[2:5]
	s_barrier
	s_setprio 0
	s_add_i32 s78, 0, 0x18000
	s_add_i32 s79, 0, 0x1c000
	v_add_u32_e32 v142, s78, v188
	v_add_u32_e32 v158, s79, v188
	ds_read_b128 v[130:133], v142
	ds_read_b128 v[134:137], v142 offset:1024
	ds_read_b128 v[138:141], v142 offset:2048
	ds_read_b128 v[142:145], v142 offset:3072
	ds_read_b128 v[146:149], v158
	ds_read_b128 v[150:153], v158 offset:1024
	ds_read_b128 v[154:157], v158 offset:2048
	ds_read_b128 v[158:161], v158 offset:3072
	s_add_u32 s0, s64, 0x80000
	s_addc_u32 s1, s65, 0
	s_mov_b32 m0, s29
	v_lshl_add_u64 v[224:225], s[0:1], 0, v[166:167]
	ds_read_b128 v[162:165], v189 offset:32768
	ds_read_b128 v[180:183], v189 offset:33792
	ds_read_b128 v[184:187], v189 offset:34816
	ds_read_b128 v[190:193], v189 offset:35840
	ds_read_b128 v[202:205], v189 offset:36864
	ds_read_b128 v[206:209], v189 offset:37888
	ds_read_b128 v[210:213], v189 offset:38912
	ds_read_b128 v[214:217], v189 offset:39936
	global_load_lds_dwordx4 v[224:225], off
	v_lshl_add_u64 v[224:225], s[0:1], 0, v[168:169]
	s_mov_b32 m0, s30
	s_nop 0
	global_load_lds_dwordx4 v[224:225], off
	s_waitcnt vmcnt(8) lgkmcnt(0)
	s_setprio 1
	s_barrier
	v_mfma_f32_16x16x32_bf16 v[126:129], v[130:133], v[162:165], v[126:129]
	v_mfma_f32_16x16x32_bf16 v[122:125], v[138:141], v[162:165], v[122:125]
	v_mfma_f32_16x16x32_bf16 v[110:113], v[130:133], v[184:187], v[110:113]
	v_mfma_f32_16x16x32_bf16 v[106:109], v[138:141], v[184:187], v[106:109]
	v_mfma_f32_16x16x32_bf16 v[98:101], v[130:133], v[202:205], v[98:101]
	v_mfma_f32_16x16x32_bf16 v[90:93], v[138:141], v[202:205], v[90:93]
	v_mfma_f32_16x16x32_bf16 v[82:85], v[130:133], v[210:213], v[82:85]
	v_mfma_f32_16x16x32_bf16 v[74:77], v[138:141], v[210:213], v[74:77]
	v_mfma_f32_16x16x32_bf16 v[126:129], v[134:137], v[180:183], v[126:129]
	v_mfma_f32_16x16x32_bf16 v[122:125], v[142:145], v[180:183], v[122:125]
	v_mfma_f32_16x16x32_bf16 v[110:113], v[134:137], v[190:193], v[110:113]
	v_mfma_f32_16x16x32_bf16 v[106:109], v[142:145], v[190:193], v[106:109]
	v_mfma_f32_16x16x32_bf16 v[98:101], v[134:137], v[206:209], v[98:101]
	v_mfma_f32_16x16x32_bf16 v[90:93], v[142:145], v[206:209], v[90:93]
	v_mfma_f32_16x16x32_bf16 v[82:85], v[134:137], v[214:217], v[82:85]
	v_mfma_f32_16x16x32_bf16 v[74:77], v[142:145], v[214:217], v[74:77]
	v_mfma_f32_16x16x32_bf16 v[118:121], v[146:149], v[162:165], v[118:121]
	v_mfma_f32_16x16x32_bf16 v[114:117], v[154:157], v[162:165], v[114:117]
	v_mfma_f32_16x16x32_bf16 v[102:105], v[146:149], v[184:187], v[102:105]
	v_mfma_f32_16x16x32_bf16 v[94:97], v[154:157], v[184:187], v[94:97]
	v_mfma_f32_16x16x32_bf16 v[86:89], v[146:149], v[202:205], v[86:89]
	v_mfma_f32_16x16x32_bf16 v[78:81], v[154:157], v[202:205], v[78:81]
	v_mfma_f32_16x16x32_bf16 v[70:73], v[146:149], v[210:213], v[70:73]
	v_mfma_f32_16x16x32_bf16 v[66:69], v[154:157], v[210:213], v[66:69]
	v_mfma_f32_16x16x32_bf16 v[118:121], v[150:153], v[180:183], v[118:121]
	v_mfma_f32_16x16x32_bf16 v[114:117], v[158:161], v[180:183], v[114:117]
	v_mfma_f32_16x16x32_bf16 v[102:105], v[150:153], v[190:193], v[102:105]
	v_mfma_f32_16x16x32_bf16 v[94:97], v[158:161], v[190:193], v[94:97]
	v_mfma_f32_16x16x32_bf16 v[86:89], v[150:153], v[206:209], v[86:89]
	v_mfma_f32_16x16x32_bf16 v[78:81], v[158:161], v[206:209], v[78:81]
	v_mfma_f32_16x16x32_bf16 v[70:73], v[150:153], v[214:217], v[70:73]
	v_mfma_f32_16x16x32_bf16 v[66:69], v[158:161], v[214:217], v[66:69]
	s_barrier
	s_setprio 0
	s_add_i32 s0, s78, s26
	v_lshl_add_u64 v[194:195], v[194:195], 0, s[16:17]
	s_mov_b32 m0, s0
	ds_read_b128 v[162:165], v189 offset:49152
	ds_read_b128 v[180:183], v189 offset:50176
	ds_read_b128 v[184:187], v189 offset:51200
	ds_read_b128 v[190:193], v189 offset:52224
	ds_read_b128 v[202:205], v189 offset:53248
	ds_read_b128 v[206:209], v189 offset:54272
	ds_read_b128 v[210:213], v189 offset:55296
	ds_read_b128 v[214:217], v189 offset:56320
	global_load_lds_dwordx4 v[194:195], off
	s_add_i32 m0, s0, 0x2000
	s_add_u32 s0, s8, 0x80080
	v_lshl_add_u64 v[194:195], v[218:219], 0, s[16:17]
	s_addc_u32 s1, s9, 0
	s_add_i32 s8, s79, s26
	global_load_lds_dwordx4 v[194:195], off
	v_lshl_add_u64 v[194:195], s[0:1], 0, v[196:197]
	s_mov_b32 m0, s8
	s_nop 0
	global_load_lds_dwordx4 v[194:195], off
	v_lshl_add_u64 v[194:195], s[0:1], 0, v[170:171]
	s_add_i32 m0, s8, 0x2000
	s_nop 0
	global_load_lds_dwordx4 v[194:195], off
	v_lshl_add_u64 v[194:195], v[220:221], 0, s[16:17]
	s_mov_b32 m0, s35
	s_nop 0
	global_load_lds_dwordx4 v[194:195], off
	v_lshl_add_u64 v[194:195], v[222:223], 0, s[16:17]
	s_mov_b32 m0, s53
	s_nop 0
	global_load_lds_dwordx4 v[194:195], off
	s_waitcnt vmcnt(8) lgkmcnt(0)
	s_setprio 1
	s_barrier
	v_mfma_f32_16x16x32_bf16 v[62:65], v[130:133], v[162:165], v[62:65]
	v_mfma_f32_16x16x32_bf16 v[58:61], v[138:141], v[162:165], v[58:61]
	v_mfma_f32_16x16x32_bf16 v[50:53], v[130:133], v[184:187], v[50:53]
	v_mfma_f32_16x16x32_bf16 v[42:45], v[138:141], v[184:187], v[42:45]
	v_mfma_f32_16x16x32_bf16 v[34:37], v[130:133], v[202:205], v[34:37]
	v_mfma_f32_16x16x32_bf16 v[26:29], v[138:141], v[202:205], v[26:29]
	v_mfma_f32_16x16x32_bf16 v[18:21], v[130:133], v[210:213], v[18:21]
	v_mfma_f32_16x16x32_bf16 v[10:13], v[138:141], v[210:213], v[10:13]
	v_mfma_f32_16x16x32_bf16 v[62:65], v[134:137], v[180:183], v[62:65]
	v_mfma_f32_16x16x32_bf16 v[58:61], v[142:145], v[180:183], v[58:61]
	v_mfma_f32_16x16x32_bf16 v[50:53], v[134:137], v[190:193], v[50:53]
	v_mfma_f32_16x16x32_bf16 v[42:45], v[142:145], v[190:193], v[42:45]
	v_mfma_f32_16x16x32_bf16 v[34:37], v[134:137], v[206:209], v[34:37]
	v_mfma_f32_16x16x32_bf16 v[26:29], v[142:145], v[206:209], v[26:29]
	v_mfma_f32_16x16x32_bf16 v[18:21], v[134:137], v[214:217], v[18:21]
	v_mfma_f32_16x16x32_bf16 v[10:13], v[142:145], v[214:217], v[10:13]
	v_mfma_f32_16x16x32_bf16 v[54:57], v[146:149], v[162:165], v[54:57]
	v_mfma_f32_16x16x32_bf16 v[46:49], v[154:157], v[162:165], v[46:49]
	v_mfma_f32_16x16x32_bf16 v[38:41], v[146:149], v[184:187], v[38:41]
	v_mfma_f32_16x16x32_bf16 v[30:33], v[154:157], v[184:187], v[30:33]
	v_mfma_f32_16x16x32_bf16 v[22:25], v[146:149], v[202:205], v[22:25]
	v_mfma_f32_16x16x32_bf16 v[14:17], v[154:157], v[202:205], v[14:17]
	v_mfma_f32_16x16x32_bf16 v[6:9], v[146:149], v[210:213], v[6:9]
	v_mfma_f32_16x16x32_bf16 v[2:5], v[154:157], v[210:213], v[2:5]
	v_mfma_f32_16x16x32_bf16 v[54:57], v[150:153], v[180:183], v[54:57]
	v_mfma_f32_16x16x32_bf16 v[46:49], v[158:161], v[180:183], v[46:49]
	v_mfma_f32_16x16x32_bf16 v[38:41], v[150:153], v[190:193], v[38:41]
	v_mfma_f32_16x16x32_bf16 v[30:33], v[158:161], v[190:193], v[30:33]
	v_mfma_f32_16x16x32_bf16 v[22:25], v[150:153], v[206:209], v[22:25]
	v_mfma_f32_16x16x32_bf16 v[14:17], v[158:161], v[206:209], v[14:17]
	v_mfma_f32_16x16x32_bf16 v[6:9], v[150:153], v[214:217], v[6:9]
	v_mfma_f32_16x16x32_bf16 v[2:5], v[158:161], v[214:217], v[2:5]
	s_barrier
	s_setprio 0
	s_add_u32 s72, s72, 0x100
	s_addc_u32 s73, s73, 0
	s_add_u32 s62, s62, 0x100
	s_addc_u32 s63, s63, 0
	s_cmp_ge_i32 s77, s69
	s_mov_b32 s8, s77
	s_cbranch_scc0 .LBB0_2357
	s_and_b64 vcc, exec, s[38:39]
	s_cbranch_vccz .LBB0_2360
	s_barrier

.LBB0_2507:
	s_add_i32 s69, s8, 2
	s_add_u32 s0, s52, 0xfff80080
	s_addc_u32 s1, s53, -1
	s_add_i32 s70, 0, 0x10000
	s_cmp_eq_u32 s66, s8
	s_cselect_b32 s59, s41, s1
	s_cselect_b32 s58, s45, s0
	s_cselect_b32 s9, s43, s68
	s_cselect_b32 s8, s65, s67
	s_add_i32 s71, 0, 0x14000
	v_add_u32_e32 v156, s70, v141
	v_add_u32_e32 v172, s71, v141
	ds_read_b128 v[144:147], v156
	ds_read_b128 v[148:151], v156 offset:1024
	ds_read_b128 v[152:155], v156 offset:2048
	ds_read_b128 v[156:159], v156 offset:3072
	ds_read_b128 v[160:163], v172
	ds_read_b128 v[164:167], v172 offset:1024
	ds_read_b128 v[168:171], v172 offset:2048
	ds_read_b128 v[172:175], v172 offset:3072
	v_lshl_add_u64 v[214:215], s[52:53], 0, v[138:139]
	s_add_i32 m0, s27, 0xc000
	ds_read_b128 v[176:179], v143
	ds_read_b128 v[180:183], v143 offset:1024
	ds_read_b128 v[184:187], v143 offset:2048
	ds_read_b128 v[188:191], v143 offset:3072
	ds_read_b128 v[192:195], v143 offset:4096
	ds_read_b128 v[202:205], v143 offset:5120
	ds_read_b128 v[206:209], v143 offset:6144
	ds_read_b128 v[210:213], v143 offset:7168
	global_load_lds_dwordx4 v[214:215], off
	v_lshl_add_u64 v[214:215], s[52:53], 0, v[136:137]
	s_add_i32 m0, s27, 0xe000
	s_nop 0
	global_load_lds_dwordx4 v[214:215], off
	s_waitcnt vmcnt(8) lgkmcnt(0)
	s_setprio 1
	s_barrier
	v_mfma_f32_16x16x32_bf16 v[126:129], v[144:147], v[176:179], v[126:129]
	v_mfma_f32_16x16x32_bf16 v[118:121], v[152:155], v[176:179], v[118:121]
	v_mfma_f32_16x16x32_bf16 v[110:113], v[144:147], v[184:187], v[110:113]
	v_mfma_f32_16x16x32_bf16 v[102:105], v[152:155], v[184:187], v[102:105]
	v_mfma_f32_16x16x32_bf16 v[94:97], v[144:147], v[192:195], v[94:97]
	v_mfma_f32_16x16x32_bf16 v[86:89], v[152:155], v[192:195], v[86:89]
	v_mfma_f32_16x16x32_bf16 v[78:81], v[144:147], v[206:209], v[78:81]
	v_mfma_f32_16x16x32_bf16 v[70:73], v[152:155], v[206:209], v[70:73]
	v_mfma_f32_16x16x32_bf16 v[126:129], v[148:151], v[180:183], v[126:129]
	v_mfma_f32_16x16x32_bf16 v[118:121], v[156:159], v[180:183], v[118:121]
	v_mfma_f32_16x16x32_bf16 v[110:113], v[148:151], v[188:191], v[110:113]
	v_mfma_f32_16x16x32_bf16 v[102:105], v[156:159], v[188:191], v[102:105]
	v_mfma_f32_16x16x32_bf16 v[94:97], v[148:151], v[202:205], v[94:97]
	v_mfma_f32_16x16x32_bf16 v[86:89], v[156:159], v[202:205], v[86:89]
	v_mfma_f32_16x16x32_bf16 v[78:81], v[148:151], v[210:213], v[78:81]
	v_mfma_f32_16x16x32_bf16 v[70:73], v[156:159], v[210:213], v[70:73]
	v_mfma_f32_16x16x32_bf16 v[122:125], v[160:163], v[176:179], v[122:125]
	v_mfma_f32_16x16x32_bf16 v[114:117], v[168:171], v[176:179], v[114:117]
	v_mfma_f32_16x16x32_bf16 v[106:109], v[160:163], v[184:187], v[106:109]
	v_mfma_f32_16x16x32_bf16 v[98:101], v[168:171], v[184:187], v[98:101]
	v_mfma_f32_16x16x32_bf16 v[90:93], v[160:163], v[192:195], v[90:93]
	v_mfma_f32_16x16x32_bf16 v[82:85], v[168:171], v[192:195], v[82:85]
	v_mfma_f32_16x16x32_bf16 v[74:77], v[160:163], v[206:209], v[74:77]
	v_mfma_f32_16x16x32_bf16 v[66:69], v[168:171], v[206:209], v[66:69]
	v_mfma_f32_16x16x32_bf16 v[122:125], v[164:167], v[180:183], v[122:125]
	v_mfma_f32_16x16x32_bf16 v[114:117], v[172:175], v[180:183], v[114:117]
	v_mfma_f32_16x16x32_bf16 v[106:109], v[164:167], v[188:191], v[106:109]
	v_mfma_f32_16x16x32_bf16 v[98:101], v[172:175], v[188:191], v[98:101]
	v_mfma_f32_16x16x32_bf16 v[90:93], v[164:167], v[202:205], v[90:93]
	v_mfma_f32_16x16x32_bf16 v[82:85], v[172:175], v[202:205], v[82:85]
	v_mfma_f32_16x16x32_bf16 v[74:77], v[164:167], v[210:213], v[74:77]
	v_mfma_f32_16x16x32_bf16 v[66:69], v[172:175], v[210:213], v[66:69]
	s_barrier
	s_setprio 0
	s_add_i32 s0, s70, s26
	v_lshl_add_u64 v[214:215], s[8:9], 0, v[196:197]
	s_mov_b32 m0, s0
	ds_read_b128 v[176:179], v143 offset:16384
	ds_read_b128 v[180:183], v143 offset:17408
	ds_read_b128 v[184:187], v143 offset:18432
	ds_read_b128 v[188:191], v143 offset:19456
	ds_read_b128 v[192:195], v143 offset:20480
	ds_read_b128 v[202:205], v143 offset:21504
	ds_read_b128 v[206:209], v143 offset:22528
	ds_read_b128 v[210:213], v143 offset:23552
	global_load_lds_dwordx4 v[214:215], off
	s_add_i32 m0, s0, 0x2000
	s_add_u32 s0, s8, 0x80000
	v_lshl_add_u64 v[216:217], s[8:9], 0, v[130:131]
	s_addc_u32 s1, s9, 0
	s_add_i32 s70, s71, s26
	global_load_lds_dwordx4 v[216:217], off
	v_lshl_add_u64 v[218:219], s[0:1], 0, v[196:197]
	s_mov_b32 m0, s70
	v_lshl_add_u64 v[220:221], s[58:59], 0, v[132:133]
	global_load_lds_dwordx4 v[218:219], off
	v_lshl_add_u64 v[218:219], s[0:1], 0, v[130:131]
	s_add_i32 m0, s70, 0x2000
	s_nop 0
	global_load_lds_dwordx4 v[218:219], off
	v_lshl_add_u64 v[218:219], s[58:59], 0, v[134:135]
	s_mov_b32 m0, s27
	s_nop 0
	global_load_lds_dwordx4 v[218:219], off
	s_mov_b32 m0, s28
	s_nop 0
	global_load_lds_dwordx4 v[220:221], off
	s_waitcnt vmcnt(8) lgkmcnt(0)
	s_setprio 1
	s_barrier
	v_mfma_f32_16x16x32_bf16 v[62:65], v[144:147], v[176:179], v[62:65]
	v_mfma_f32_16x16x32_bf16 v[54:57], v[152:155], v[176:179], v[54:57]
	v_mfma_f32_16x16x32_bf16 v[46:49], v[144:147], v[184:187], v[46:49]
	v_mfma_f32_16x16x32_bf16 v[38:41], v[152:155], v[184:187], v[38:41]
	v_mfma_f32_16x16x32_bf16 v[30:33], v[144:147], v[192:195], v[30:33]
	v_mfma_f32_16x16x32_bf16 v[22:25], v[152:155], v[192:195], v[22:25]
	v_mfma_f32_16x16x32_bf16 v[14:17], v[144:147], v[206:209], v[14:17]
	v_mfma_f32_16x16x32_bf16 v[6:9], v[152:155], v[206:209], v[6:9]
	v_mfma_f32_16x16x32_bf16 v[62:65], v[148:151], v[180:183], v[62:65]
	v_mfma_f32_16x16x32_bf16 v[54:57], v[156:159], v[180:183], v[54:57]
	v_mfma_f32_16x16x32_bf16 v[46:49], v[148:151], v[188:191], v[46:49]
	v_mfma_f32_16x16x32_bf16 v[38:41], v[156:159], v[188:191], v[38:41]
	v_mfma_f32_16x16x32_bf16 v[30:33], v[148:151], v[202:205], v[30:33]
	v_mfma_f32_16x16x32_bf16 v[22:25], v[156:159], v[202:205], v[22:25]
	v_mfma_f32_16x16x32_bf16 v[14:17], v[148:151], v[210:213], v[14:17]
	v_mfma_f32_16x16x32_bf16 v[6:9], v[156:159], v[210:213], v[6:9]
	v_mfma_f32_16x16x32_bf16 v[58:61], v[160:163], v[176:179], v[58:61]
	v_mfma_f32_16x16x32_bf16 v[50:53], v[168:171], v[176:179], v[50:53]
	v_mfma_f32_16x16x32_bf16 v[42:45], v[160:163], v[184:187], v[42:45]
	v_mfma_f32_16x16x32_bf16 v[34:37], v[168:171], v[184:187], v[34:37]
	v_mfma_f32_16x16x32_bf16 v[26:29], v[160:163], v[192:195], v[26:29]
	v_mfma_f32_16x16x32_bf16 v[18:21], v[168:171], v[192:195], v[18:21]
	v_mfma_f32_16x16x32_bf16 v[10:13], v[160:163], v[206:209], v[10:13]
	v_mfma_f32_16x16x32_bf16 v[2:5], v[168:171], v[206:209], v[2:5]
	v_mfma_f32_16x16x32_bf16 v[58:61], v[164:167], v[180:183], v[58:61]
	v_mfma_f32_16x16x32_bf16 v[50:53], v[172:175], v[180:183], v[50:53]
	v_mfma_f32_16x16x32_bf16 v[42:45], v[164:167], v[188:191], v[42:45]
	v_mfma_f32_16x16x32_bf16 v[34:37], v[172:175], v[188:191], v[34:37]
	v_mfma_f32_16x16x32_bf16 v[26:29], v[164:167], v[202:205], v[26:29]
	v_mfma_f32_16x16x32_bf16 v[18:21], v[172:175], v[202:205], v[18:21]
	v_mfma_f32_16x16x32_bf16 v[10:13], v[164:167], v[210:213], v[10:13]
	v_mfma_f32_16x16x32_bf16 v[2:5], v[172:175], v[210:213], v[2:5]
	s_barrier
	s_setprio 0
	s_add_i32 s70, 0, 0x18000
	s_add_i32 s71, 0, 0x1c000
	v_add_u32_e32 v156, s70, v141
	v_add_u32_e32 v172, s71, v141
	ds_read_b128 v[144:147], v156
	ds_read_b128 v[148:151], v156 offset:1024
	ds_read_b128 v[152:155], v156 offset:2048
	ds_read_b128 v[156:159], v156 offset:3072
	ds_read_b128 v[160:163], v172
	ds_read_b128 v[164:167], v172 offset:1024
	ds_read_b128 v[168:171], v172 offset:2048
	ds_read_b128 v[172:175], v172 offset:3072
	s_add_u32 s0, s58, 0x80000
	s_addc_u32 s1, s59, 0
	s_mov_b32 m0, s29
	v_lshl_add_u64 v[222:223], s[0:1], 0, v[134:135]
	ds_read_b128 v[176:179], v143 offset:32768
	ds_read_b128 v[180:183], v143 offset:33792
	ds_read_b128 v[184:187], v143 offset:34816
	ds_read_b128 v[188:191], v143 offset:35840
	ds_read_b128 v[192:195], v143 offset:36864
	ds_read_b128 v[202:205], v143 offset:37888
	ds_read_b128 v[206:209], v143 offset:38912
	ds_read_b128 v[210:213], v143 offset:39936
	global_load_lds_dwordx4 v[222:223], off
	v_lshl_add_u64 v[222:223], s[0:1], 0, v[132:133]
	s_mov_b32 m0, s30
	s_nop 0
	global_load_lds_dwordx4 v[222:223], off
	s_waitcnt vmcnt(8) lgkmcnt(0)
	s_setprio 1
	s_barrier
	v_mfma_f32_16x16x32_bf16 v[126:129], v[144:147], v[176:179], v[126:129]
	v_mfma_f32_16x16x32_bf16 v[118:121], v[152:155], v[176:179], v[118:121]
	v_mfma_f32_16x16x32_bf16 v[110:113], v[144:147], v[184:187], v[110:113]
	v_mfma_f32_16x16x32_bf16 v[102:105], v[152:155], v[184:187], v[102:105]
	v_mfma_f32_16x16x32_bf16 v[94:97], v[144:147], v[192:195], v[94:97]
	v_mfma_f32_16x16x32_bf16 v[86:89], v[152:155], v[192:195], v[86:89]
	v_mfma_f32_16x16x32_bf16 v[78:81], v[144:147], v[206:209], v[78:81]
	v_mfma_f32_16x16x32_bf16 v[70:73], v[152:155], v[206:209], v[70:73]
	v_mfma_f32_16x16x32_bf16 v[126:129], v[148:151], v[180:183], v[126:129]
	v_mfma_f32_16x16x32_bf16 v[118:121], v[156:159], v[180:183], v[118:121]
	v_mfma_f32_16x16x32_bf16 v[110:113], v[148:151], v[188:191], v[110:113]
	v_mfma_f32_16x16x32_bf16 v[102:105], v[156:159], v[188:191], v[102:105]
	v_mfma_f32_16x16x32_bf16 v[94:97], v[148:151], v[202:205], v[94:97]
	v_mfma_f32_16x16x32_bf16 v[86:89], v[156:159], v[202:205], v[86:89]
	v_mfma_f32_16x16x32_bf16 v[78:81], v[148:151], v[210:213], v[78:81]
	v_mfma_f32_16x16x32_bf16 v[70:73], v[156:159], v[210:213], v[70:73]
	v_mfma_f32_16x16x32_bf16 v[122:125], v[160:163], v[176:179], v[122:125]
	v_mfma_f32_16x16x32_bf16 v[114:117], v[168:171], v[176:179], v[114:117]
	v_mfma_f32_16x16x32_bf16 v[106:109], v[160:163], v[184:187], v[106:109]
	v_mfma_f32_16x16x32_bf16 v[98:101], v[168:171], v[184:187], v[98:101]
	v_mfma_f32_16x16x32_bf16 v[90:93], v[160:163], v[192:195], v[90:93]
	v_mfma_f32_16x16x32_bf16 v[82:85], v[168:171], v[192:195], v[82:85]
	v_mfma_f32_16x16x32_bf16 v[74:77], v[160:163], v[206:209], v[74:77]
	v_mfma_f32_16x16x32_bf16 v[66:69], v[168:171], v[206:209], v[66:69]
	v_mfma_f32_16x16x32_bf16 v[122:125], v[164:167], v[180:183], v[122:125]
	v_mfma_f32_16x16x32_bf16 v[114:117], v[172:175], v[180:183], v[114:117]
	v_mfma_f32_16x16x32_bf16 v[106:109], v[164:167], v[188:191], v[106:109]
	v_mfma_f32_16x16x32_bf16 v[98:101], v[172:175], v[188:191], v[98:101]
	v_mfma_f32_16x16x32_bf16 v[90:93], v[164:167], v[202:205], v[90:93]
	v_mfma_f32_16x16x32_bf16 v[82:85], v[172:175], v[202:205], v[82:85]
	v_mfma_f32_16x16x32_bf16 v[74:77], v[164:167], v[210:213], v[74:77]
	v_mfma_f32_16x16x32_bf16 v[66:69], v[172:175], v[210:213], v[66:69]
	s_barrier
	s_setprio 0
	s_add_i32 s0, s70, s26
	v_lshl_add_u64 v[214:215], v[214:215], 0, s[16:17]
	s_mov_b32 m0, s0
	ds_read_b128 v[176:179], v143 offset:49152
	ds_read_b128 v[180:183], v143 offset:50176
	ds_read_b128 v[184:187], v143 offset:51200
	ds_read_b128 v[188:191], v143 offset:52224
	ds_read_b128 v[192:195], v143 offset:53248
	ds_read_b128 v[202:205], v143 offset:54272
	ds_read_b128 v[206:209], v143 offset:55296
	ds_read_b128 v[210:213], v143 offset:56320
	global_load_lds_dwordx4 v[214:215], off
	s_add_i32 m0, s0, 0x2000
	s_add_u32 s0, s8, 0x80080
	v_lshl_add_u64 v[214:215], v[216:217], 0, s[16:17]
	s_addc_u32 s1, s9, 0
	s_add_i32 s8, s71, s26
	global_load_lds_dwordx4 v[214:215], off
	v_lshl_add_u64 v[214:215], s[0:1], 0, v[196:197]
	s_mov_b32 m0, s8
	s_nop 0
	global_load_lds_dwordx4 v[214:215], off
	v_lshl_add_u64 v[214:215], s[0:1], 0, v[130:131]
	s_add_i32 m0, s8, 0x2000
	s_nop 0
	global_load_lds_dwordx4 v[214:215], off
	v_lshl_add_u64 v[214:215], v[218:219], 0, s[16:17]
	s_mov_b32 m0, s31
	s_nop 0
	global_load_lds_dwordx4 v[214:215], off
	v_lshl_add_u64 v[214:215], v[220:221], 0, s[16:17]
	s_mov_b32 m0, s34
	s_nop 0
	global_load_lds_dwordx4 v[214:215], off
	s_waitcnt vmcnt(8) lgkmcnt(0)
	s_setprio 1
	s_barrier
	v_mfma_f32_16x16x32_bf16 v[62:65], v[144:147], v[176:179], v[62:65]
	v_mfma_f32_16x16x32_bf16 v[54:57], v[152:155], v[176:179], v[54:57]
	v_mfma_f32_16x16x32_bf16 v[46:49], v[144:147], v[184:187], v[46:49]
	v_mfma_f32_16x16x32_bf16 v[38:41], v[152:155], v[184:187], v[38:41]
	v_mfma_f32_16x16x32_bf16 v[30:33], v[144:147], v[192:195], v[30:33]
	v_mfma_f32_16x16x32_bf16 v[22:25], v[152:155], v[192:195], v[22:25]
	v_mfma_f32_16x16x32_bf16 v[14:17], v[144:147], v[206:209], v[14:17]
	v_mfma_f32_16x16x32_bf16 v[6:9], v[152:155], v[206:209], v[6:9]
	v_mfma_f32_16x16x32_bf16 v[62:65], v[148:151], v[180:183], v[62:65]
	v_mfma_f32_16x16x32_bf16 v[54:57], v[156:159], v[180:183], v[54:57]
	v_mfma_f32_16x16x32_bf16 v[46:49], v[148:151], v[188:191], v[46:49]
	v_mfma_f32_16x16x32_bf16 v[38:41], v[156:159], v[188:191], v[38:41]
	v_mfma_f32_16x16x32_bf16 v[30:33], v[148:151], v[202:205], v[30:33]
	v_mfma_f32_16x16x32_bf16 v[22:25], v[156:159], v[202:205], v[22:25]
	v_mfma_f32_16x16x32_bf16 v[14:17], v[148:151], v[210:213], v[14:17]
	v_mfma_f32_16x16x32_bf16 v[6:9], v[156:159], v[210:213], v[6:9]
	v_mfma_f32_16x16x32_bf16 v[58:61], v[160:163], v[176:179], v[58:61]
	v_mfma_f32_16x16x32_bf16 v[50:53], v[168:171], v[176:179], v[50:53]
	v_mfma_f32_16x16x32_bf16 v[42:45], v[160:163], v[184:187], v[42:45]
	v_mfma_f32_16x16x32_bf16 v[34:37], v[168:171], v[184:187], v[34:37]
	v_mfma_f32_16x16x32_bf16 v[26:29], v[160:163], v[192:195], v[26:29]
	v_mfma_f32_16x16x32_bf16 v[18:21], v[168:171], v[192:195], v[18:21]
	v_mfma_f32_16x16x32_bf16 v[10:13], v[160:163], v[206:209], v[10:13]
	v_mfma_f32_16x16x32_bf16 v[2:5], v[168:171], v[206:209], v[2:5]
	v_mfma_f32_16x16x32_bf16 v[58:61], v[164:167], v[180:183], v[58:61]
	v_mfma_f32_16x16x32_bf16 v[50:53], v[172:175], v[180:183], v[50:53]
	v_mfma_f32_16x16x32_bf16 v[42:45], v[164:167], v[188:191], v[42:45]
	v_mfma_f32_16x16x32_bf16 v[34:37], v[172:175], v[188:191], v[34:37]
	v_mfma_f32_16x16x32_bf16 v[26:29], v[164:167], v[202:205], v[26:29]
	v_mfma_f32_16x16x32_bf16 v[18:21], v[172:175], v[202:205], v[18:21]
	v_mfma_f32_16x16x32_bf16 v[10:13], v[164:167], v[210:213], v[10:13]
	v_mfma_f32_16x16x32_bf16 v[2:5], v[172:175], v[210:213], v[2:5]
	s_barrier
	s_setprio 0
	s_add_u32 s67, s67, 0x100
	s_addc_u32 s68, s68, 0
	s_add_u32 s52, s52, 0x100
	s_addc_u32 s53, s53, 0
	s_cmp_ge_i32 s69, s62
	s_mov_b32 s8, s69
	s_cbranch_scc0 .LBB0_2507
	s_and_b64 vcc, exec, s[38:39]
	s_cbranch_vccz .LBB0_2510
	s_barrier

.LBB0_2588:
	s_add_i32 s72, s48, 2
	s_add_u32 s8, s46, 0x100
	s_addc_u32 s9, s47, 0
	s_add_i32 s0, 0, 0x10000
	s_cmp_eq_u32 s41, s48
	s_cselect_b32 s51, s43, s9
	s_cselect_b32 s50, s42, s8
	s_cselect_b32 s49, s45, s71
	s_cselect_b32 s48, s44, s70
	s_add_i32 s73, 0, 0x14000
	v_add_u32_e32 v142, s0, v188
	v_add_u32_e32 v172, s73, v188
	ds_read_b128 v[130:133], v142
	ds_read_b128 v[134:137], v142 offset:1024
	ds_read_b128 v[138:141], v142 offset:2048
	ds_read_b128 v[142:145], v142 offset:3072
	ds_read_b128 v[146:149], v172
	ds_read_b128 v[164:167], v172 offset:1024
	ds_read_b128 v[168:171], v172 offset:2048
	ds_read_b128 v[172:175], v172 offset:3072
	v_lshl_add_u64 v[194:195], s[46:47], 0, v[162:163]
	s_add_i32 m0, s27, 0xc000
	ds_read_b128 v[176:179], v189
	ds_read_b128 v[180:183], v189 offset:1024
	ds_read_b128 v[184:187], v189 offset:2048
	ds_read_b128 v[190:193], v189 offset:3072
	ds_read_b128 v[202:205], v189 offset:4096
	ds_read_b128 v[206:209], v189 offset:5120
	ds_read_b128 v[210:213], v189 offset:6144
	ds_read_b128 v[214:217], v189 offset:7168
	global_load_lds_dwordx4 v[194:195], off
	v_lshl_add_u64 v[194:195], s[46:47], 0, v[160:161]
	s_add_i32 m0, s27, 0xe000
	s_nop 0
	global_load_lds_dwordx4 v[194:195], off
	s_waitcnt vmcnt(8) lgkmcnt(0)
	s_setprio 1
	s_barrier
	v_mfma_f32_16x16x32_bf16 v[126:129], v[130:133], v[176:179], v[126:129]
	v_mfma_f32_16x16x32_bf16 v[122:125], v[138:141], v[176:179], v[122:125]
	v_mfma_f32_16x16x32_bf16 v[110:113], v[130:133], v[184:187], v[110:113]
	v_mfma_f32_16x16x32_bf16 v[106:109], v[138:141], v[184:187], v[106:109]
	v_mfma_f32_16x16x32_bf16 v[98:101], v[130:133], v[202:205], v[98:101]
	v_mfma_f32_16x16x32_bf16 v[90:93], v[138:141], v[202:205], v[90:93]
	v_mfma_f32_16x16x32_bf16 v[82:85], v[130:133], v[210:213], v[82:85]
	v_mfma_f32_16x16x32_bf16 v[74:77], v[138:141], v[210:213], v[74:77]
	v_mfma_f32_16x16x32_bf16 v[126:129], v[134:137], v[180:183], v[126:129]
	v_mfma_f32_16x16x32_bf16 v[122:125], v[142:145], v[180:183], v[122:125]
	v_mfma_f32_16x16x32_bf16 v[110:113], v[134:137], v[190:193], v[110:113]
	v_mfma_f32_16x16x32_bf16 v[106:109], v[142:145], v[190:193], v[106:109]
	v_mfma_f32_16x16x32_bf16 v[98:101], v[134:137], v[206:209], v[98:101]
	v_mfma_f32_16x16x32_bf16 v[90:93], v[142:145], v[206:209], v[90:93]
	v_mfma_f32_16x16x32_bf16 v[82:85], v[134:137], v[214:217], v[82:85]
	v_mfma_f32_16x16x32_bf16 v[74:77], v[142:145], v[214:217], v[74:77]
	v_mfma_f32_16x16x32_bf16 v[118:121], v[146:149], v[176:179], v[118:121]
	v_mfma_f32_16x16x32_bf16 v[114:117], v[168:171], v[176:179], v[114:117]
	v_mfma_f32_16x16x32_bf16 v[102:105], v[146:149], v[184:187], v[102:105]
	v_mfma_f32_16x16x32_bf16 v[94:97], v[168:171], v[184:187], v[94:97]
	v_mfma_f32_16x16x32_bf16 v[86:89], v[146:149], v[202:205], v[86:89]
	v_mfma_f32_16x16x32_bf16 v[78:81], v[168:171], v[202:205], v[78:81]
	v_mfma_f32_16x16x32_bf16 v[70:73], v[146:149], v[210:213], v[70:73]
	v_mfma_f32_16x16x32_bf16 v[66:69], v[168:171], v[210:213], v[66:69]
	v_mfma_f32_16x16x32_bf16 v[118:121], v[164:167], v[180:183], v[118:121]
	v_mfma_f32_16x16x32_bf16 v[114:117], v[172:175], v[180:183], v[114:117]
	v_mfma_f32_16x16x32_bf16 v[102:105], v[164:167], v[190:193], v[102:105]
	v_mfma_f32_16x16x32_bf16 v[94:97], v[172:175], v[190:193], v[94:97]
	v_mfma_f32_16x16x32_bf16 v[86:89], v[164:167], v[206:209], v[86:89]
	v_mfma_f32_16x16x32_bf16 v[78:81], v[172:175], v[206:209], v[78:81]
	v_mfma_f32_16x16x32_bf16 v[70:73], v[164:167], v[214:217], v[70:73]
	v_mfma_f32_16x16x32_bf16 v[66:69], v[172:175], v[214:217], v[66:69]
	s_barrier
	s_setprio 0
	s_add_i32 s0, s0, s26
	v_lshl_add_u64 v[194:195], s[48:49], 0, v[196:197]
	s_mov_b32 m0, s0
	ds_read_b128 v[176:179], v189 offset:16384
	ds_read_b128 v[180:183], v189 offset:17408
	ds_read_b128 v[184:187], v189 offset:18432
	ds_read_b128 v[190:193], v189 offset:19456
	ds_read_b128 v[202:205], v189 offset:20480
	ds_read_b128 v[206:209], v189 offset:21504
	ds_read_b128 v[210:213], v189 offset:22528
	ds_read_b128 v[214:217], v189 offset:23552
	global_load_lds_dwordx4 v[194:195], off
	s_add_i32 m0, s0, 0x2000
	s_add_u32 s0, s48, 0x158000
	v_lshl_add_u64 v[218:219], s[48:49], 0, v[154:155]
	s_addc_u32 s1, s49, 0
	s_add_i32 s46, s73, s26
	global_load_lds_dwordx4 v[218:219], off
	v_lshl_add_u64 v[220:221], s[0:1], 0, v[196:197]
	s_mov_b32 m0, s46
	v_lshl_add_u64 v[222:223], s[50:51], 0, v[152:153]
	global_load_lds_dwordx4 v[220:221], off
	v_lshl_add_u64 v[220:221], s[0:1], 0, v[154:155]
	s_add_i32 m0, s46, 0x2000
	s_nop 0
	global_load_lds_dwordx4 v[220:221], off
	v_lshl_add_u64 v[220:221], s[50:51], 0, v[150:151]
	s_mov_b32 m0, s27
	s_nop 0
	global_load_lds_dwordx4 v[220:221], off
	s_mov_b32 m0, s30
	s_nop 0
	global_load_lds_dwordx4 v[222:223], off
	s_waitcnt vmcnt(8) lgkmcnt(0)
	s_setprio 1
	s_barrier
	v_mfma_f32_16x16x32_bf16 v[62:65], v[130:133], v[176:179], v[62:65]
	v_mfma_f32_16x16x32_bf16 v[58:61], v[138:141], v[176:179], v[58:61]
	v_mfma_f32_16x16x32_bf16 v[50:53], v[130:133], v[184:187], v[50:53]
	v_mfma_f32_16x16x32_bf16 v[42:45], v[138:141], v[184:187], v[42:45]
	v_mfma_f32_16x16x32_bf16 v[34:37], v[130:133], v[202:205], v[34:37]
	v_mfma_f32_16x16x32_bf16 v[26:29], v[138:141], v[202:205], v[26:29]
	v_mfma_f32_16x16x32_bf16 v[18:21], v[130:133], v[210:213], v[18:21]
	v_mfma_f32_16x16x32_bf16 v[10:13], v[138:141], v[210:213], v[10:13]
	v_mfma_f32_16x16x32_bf16 v[62:65], v[134:137], v[180:183], v[62:65]
	v_mfma_f32_16x16x32_bf16 v[58:61], v[142:145], v[180:183], v[58:61]
	v_mfma_f32_16x16x32_bf16 v[50:53], v[134:137], v[190:193], v[50:53]
	v_mfma_f32_16x16x32_bf16 v[42:45], v[142:145], v[190:193], v[42:45]
	v_mfma_f32_16x16x32_bf16 v[34:37], v[134:137], v[206:209], v[34:37]
	v_mfma_f32_16x16x32_bf16 v[26:29], v[142:145], v[206:209], v[26:29]
	v_mfma_f32_16x16x32_bf16 v[18:21], v[134:137], v[214:217], v[18:21]
	v_mfma_f32_16x16x32_bf16 v[10:13], v[142:145], v[214:217], v[10:13]
	v_mfma_f32_16x16x32_bf16 v[54:57], v[146:149], v[176:179], v[54:57]
	v_mfma_f32_16x16x32_bf16 v[46:49], v[168:171], v[176:179], v[46:49]
	v_mfma_f32_16x16x32_bf16 v[38:41], v[146:149], v[184:187], v[38:41]
	v_mfma_f32_16x16x32_bf16 v[30:33], v[168:171], v[184:187], v[30:33]
	v_mfma_f32_16x16x32_bf16 v[22:25], v[146:149], v[202:205], v[22:25]
	v_mfma_f32_16x16x32_bf16 v[14:17], v[168:171], v[202:205], v[14:17]
	v_mfma_f32_16x16x32_bf16 v[6:9], v[146:149], v[210:213], v[6:9]
	v_mfma_f32_16x16x32_bf16 v[2:5], v[168:171], v[210:213], v[2:5]
	v_mfma_f32_16x16x32_bf16 v[54:57], v[164:167], v[180:183], v[54:57]
	v_mfma_f32_16x16x32_bf16 v[46:49], v[172:175], v[180:183], v[46:49]
	v_mfma_f32_16x16x32_bf16 v[38:41], v[164:167], v[190:193], v[38:41]
	v_mfma_f32_16x16x32_bf16 v[30:33], v[172:175], v[190:193], v[30:33]
	v_mfma_f32_16x16x32_bf16 v[22:25], v[164:167], v[206:209], v[22:25]
	v_mfma_f32_16x16x32_bf16 v[14:17], v[172:175], v[206:209], v[14:17]
	v_mfma_f32_16x16x32_bf16 v[6:9], v[164:167], v[214:217], v[6:9]
	v_mfma_f32_16x16x32_bf16 v[2:5], v[172:175], v[214:217], v[2:5]
	s_barrier
	s_setprio 0
	s_add_i32 s46, 0, 0x18000
	s_add_i32 s47, 0, 0x1c000
	v_add_u32_e32 v142, s46, v188
	v_add_u32_e32 v172, s47, v188
	ds_read_b128 v[130:133], v142
	ds_read_b128 v[134:137], v142 offset:1024
	ds_read_b128 v[138:141], v142 offset:2048
	ds_read_b128 v[142:145], v142 offset:3072
	ds_read_b128 v[146:149], v172
	ds_read_b128 v[164:167], v172 offset:1024
	ds_read_b128 v[168:171], v172 offset:2048
	ds_read_b128 v[172:175], v172 offset:3072
	s_add_u32 s0, s50, 0x158000
	s_addc_u32 s1, s51, 0
	s_mov_b32 m0, s31
	v_lshl_add_u64 v[224:225], s[0:1], 0, v[150:151]
	ds_read_b128 v[176:179], v189 offset:32768
	ds_read_b128 v[180:183], v189 offset:33792
	ds_read_b128 v[184:187], v189 offset:34816
	ds_read_b128 v[190:193], v189 offset:35840
	ds_read_b128 v[202:205], v189 offset:36864
	ds_read_b128 v[206:209], v189 offset:37888
	ds_read_b128 v[210:213], v189 offset:38912
	ds_read_b128 v[214:217], v189 offset:39936
	global_load_lds_dwordx4 v[224:225], off
	v_lshl_add_u64 v[224:225], s[0:1], 0, v[152:153]
	s_mov_b32 m0, s34
	s_nop 0
	global_load_lds_dwordx4 v[224:225], off
	s_waitcnt vmcnt(8) lgkmcnt(0)
	s_setprio 1
	s_barrier
	v_mfma_f32_16x16x32_bf16 v[126:129], v[130:133], v[176:179], v[126:129]
	v_mfma_f32_16x16x32_bf16 v[122:125], v[138:141], v[176:179], v[122:125]
	v_mfma_f32_16x16x32_bf16 v[110:113], v[130:133], v[184:187], v[110:113]
	v_mfma_f32_16x16x32_bf16 v[106:109], v[138:141], v[184:187], v[106:109]
	v_mfma_f32_16x16x32_bf16 v[98:101], v[130:133], v[202:205], v[98:101]
	v_mfma_f32_16x16x32_bf16 v[90:93], v[138:141], v[202:205], v[90:93]
	v_mfma_f32_16x16x32_bf16 v[82:85], v[130:133], v[210:213], v[82:85]
	v_mfma_f32_16x16x32_bf16 v[74:77], v[138:141], v[210:213], v[74:77]
	v_mfma_f32_16x16x32_bf16 v[126:129], v[134:137], v[180:183], v[126:129]
	v_mfma_f32_16x16x32_bf16 v[122:125], v[142:145], v[180:183], v[122:125]
	v_mfma_f32_16x16x32_bf16 v[110:113], v[134:137], v[190:193], v[110:113]
	v_mfma_f32_16x16x32_bf16 v[106:109], v[142:145], v[190:193], v[106:109]
	v_mfma_f32_16x16x32_bf16 v[98:101], v[134:137], v[206:209], v[98:101]
	v_mfma_f32_16x16x32_bf16 v[90:93], v[142:145], v[206:209], v[90:93]
	v_mfma_f32_16x16x32_bf16 v[82:85], v[134:137], v[214:217], v[82:85]
	v_mfma_f32_16x16x32_bf16 v[74:77], v[142:145], v[214:217], v[74:77]
	v_mfma_f32_16x16x32_bf16 v[118:121], v[146:149], v[176:179], v[118:121]
	v_mfma_f32_16x16x32_bf16 v[114:117], v[168:171], v[176:179], v[114:117]
	v_mfma_f32_16x16x32_bf16 v[102:105], v[146:149], v[184:187], v[102:105]
	v_mfma_f32_16x16x32_bf16 v[94:97], v[168:171], v[184:187], v[94:97]
	v_mfma_f32_16x16x32_bf16 v[86:89], v[146:149], v[202:205], v[86:89]
	v_mfma_f32_16x16x32_bf16 v[78:81], v[168:171], v[202:205], v[78:81]
	v_mfma_f32_16x16x32_bf16 v[70:73], v[146:149], v[210:213], v[70:73]
	v_mfma_f32_16x16x32_bf16 v[66:69], v[168:171], v[210:213], v[66:69]
	v_mfma_f32_16x16x32_bf16 v[118:121], v[164:167], v[180:183], v[118:121]
	v_mfma_f32_16x16x32_bf16 v[114:117], v[172:175], v[180:183], v[114:117]
	v_mfma_f32_16x16x32_bf16 v[102:105], v[164:167], v[190:193], v[102:105]
	v_mfma_f32_16x16x32_bf16 v[94:97], v[172:175], v[190:193], v[94:97]
	v_mfma_f32_16x16x32_bf16 v[86:89], v[164:167], v[206:209], v[86:89]
	v_mfma_f32_16x16x32_bf16 v[78:81], v[172:175], v[206:209], v[78:81]
	v_mfma_f32_16x16x32_bf16 v[70:73], v[164:167], v[214:217], v[70:73]
	v_mfma_f32_16x16x32_bf16 v[66:69], v[172:175], v[214:217], v[66:69]
	s_barrier
	s_setprio 0
	s_add_i32 s0, s46, s26
	v_lshl_add_u64 v[194:195], v[194:195], 0, s[16:17]
	s_mov_b32 m0, s0
	ds_read_b128 v[176:179], v189 offset:49152
	ds_read_b128 v[180:183], v189 offset:50176
	ds_read_b128 v[184:187], v189 offset:51200
	ds_read_b128 v[190:193], v189 offset:52224
	ds_read_b128 v[202:205], v189 offset:53248
	ds_read_b128 v[206:209], v189 offset:54272
	ds_read_b128 v[210:213], v189 offset:55296
	ds_read_b128 v[214:217], v189 offset:56320
	global_load_lds_dwordx4 v[194:195], off
	s_add_i32 m0, s0, 0x2000
	s_add_u32 s0, s48, 0x158080
	v_lshl_add_u64 v[194:195], v[218:219], 0, s[16:17]
	s_addc_u32 s1, s49, 0
	s_add_i32 s46, s47, s26
	global_load_lds_dwordx4 v[194:195], off
	v_lshl_add_u64 v[194:195], s[0:1], 0, v[196:197]
	s_mov_b32 m0, s46
	s_nop 0
	global_load_lds_dwordx4 v[194:195], off
	v_lshl_add_u64 v[194:195], s[0:1], 0, v[154:155]
	s_add_i32 m0, s46, 0x2000
	s_nop 0
	global_load_lds_dwordx4 v[194:195], off
	v_lshl_add_u64 v[194:195], v[220:221], 0, s[16:17]
	s_mov_b32 m0, s53
	s_nop 0
	global_load_lds_dwordx4 v[194:195], off
	v_lshl_add_u64 v[194:195], v[222:223], 0, s[16:17]
	s_mov_b32 m0, s58
	s_nop 0
	global_load_lds_dwordx4 v[194:195], off
	s_waitcnt vmcnt(8) lgkmcnt(0)
	s_setprio 1
	s_barrier
	v_mfma_f32_16x16x32_bf16 v[62:65], v[130:133], v[176:179], v[62:65]
	v_mfma_f32_16x16x32_bf16 v[58:61], v[138:141], v[176:179], v[58:61]
	v_mfma_f32_16x16x32_bf16 v[50:53], v[130:133], v[184:187], v[50:53]
	v_mfma_f32_16x16x32_bf16 v[42:45], v[138:141], v[184:187], v[42:45]
	v_mfma_f32_16x16x32_bf16 v[34:37], v[130:133], v[202:205], v[34:37]
	v_mfma_f32_16x16x32_bf16 v[26:29], v[138:141], v[202:205], v[26:29]
	v_mfma_f32_16x16x32_bf16 v[18:21], v[130:133], v[210:213], v[18:21]
	v_mfma_f32_16x16x32_bf16 v[10:13], v[138:141], v[210:213], v[10:13]
	v_mfma_f32_16x16x32_bf16 v[62:65], v[134:137], v[180:183], v[62:65]
	v_mfma_f32_16x16x32_bf16 v[58:61], v[142:145], v[180:183], v[58:61]
	v_mfma_f32_16x16x32_bf16 v[50:53], v[134:137], v[190:193], v[50:53]
	v_mfma_f32_16x16x32_bf16 v[42:45], v[142:145], v[190:193], v[42:45]
	v_mfma_f32_16x16x32_bf16 v[34:37], v[134:137], v[206:209], v[34:37]
	v_mfma_f32_16x16x32_bf16 v[26:29], v[142:145], v[206:209], v[26:29]
	v_mfma_f32_16x16x32_bf16 v[18:21], v[134:137], v[214:217], v[18:21]
	v_mfma_f32_16x16x32_bf16 v[10:13], v[142:145], v[214:217], v[10:13]
	v_mfma_f32_16x16x32_bf16 v[54:57], v[146:149], v[176:179], v[54:57]
	v_mfma_f32_16x16x32_bf16 v[46:49], v[168:171], v[176:179], v[46:49]
	v_mfma_f32_16x16x32_bf16 v[38:41], v[146:149], v[184:187], v[38:41]
	v_mfma_f32_16x16x32_bf16 v[30:33], v[168:171], v[184:187], v[30:33]
	v_mfma_f32_16x16x32_bf16 v[22:25], v[146:149], v[202:205], v[22:25]
	v_mfma_f32_16x16x32_bf16 v[14:17], v[168:171], v[202:205], v[14:17]
	v_mfma_f32_16x16x32_bf16 v[6:9], v[146:149], v[210:213], v[6:9]
	v_mfma_f32_16x16x32_bf16 v[2:5], v[168:171], v[210:213], v[2:5]
	v_mfma_f32_16x16x32_bf16 v[54:57], v[164:167], v[180:183], v[54:57]
	v_mfma_f32_16x16x32_bf16 v[46:49], v[172:175], v[180:183], v[46:49]
	v_mfma_f32_16x16x32_bf16 v[38:41], v[164:167], v[190:193], v[38:41]
	v_mfma_f32_16x16x32_bf16 v[30:33], v[172:175], v[190:193], v[30:33]
	v_mfma_f32_16x16x32_bf16 v[22:25], v[164:167], v[206:209], v[22:25]
	v_mfma_f32_16x16x32_bf16 v[14:17], v[172:175], v[206:209], v[14:17]
	v_mfma_f32_16x16x32_bf16 v[6:9], v[164:167], v[214:217], v[6:9]
	v_mfma_f32_16x16x32_bf16 v[2:5], v[172:175], v[214:217], v[2:5]
	s_barrier
	s_setprio 0
	s_add_u32 s70, s70, 0x100
	s_addc_u32 s71, s71, 0
	s_cmp_ge_i32 s72, s69
	s_mov_b64 s[46:47], s[8:9]
	s_mov_b32 s48, s72
	s_cbranch_scc0 .LBB0_2588
	s_and_b64 vcc, exec, s[28:29]
	s_cbranch_vccz .LBB0_2591
	s_barrier
